# ret_proj gate-tile epilogue: silu on row pairs with packed f32 mul/add/fma (same IEEE divide sequence), v_cvt_pk_bf16_f32 rounding, LDS-staged 16-byte row stores
# baseline (speedup 1.0000x reference)
.LBB0_1018:
	s_add_i32 s3, s1, 1
	s_cmp_lt_u32 s1, 15
	s_cselect_b32 s1, s3, s1
	s_lshl_b32 s12, s1, 6
	s_lshl_b64 s[10:11], s[12:13], 1
	s_barrier
	s_waitcnt vmcnt(0)
	ds_write_b128 v204, v[174:177]
	ds_write_b128 v204, v[170:173] offset:4608
	ds_write_b128 v204, v[166:169] offset:9216
	ds_write_b128 v204, v[162:165] offset:13824
	ds_write_b128 v204, v[158:161] offset:18432
	ds_write_b128 v204, v[154:157] offset:23040
	ds_write_b128 v204, v[150:153] offset:27648
	ds_write_b128 v204, v[146:149] offset:32256
	ds_write_b128 v204, v[142:145] offset:36864
	ds_write_b128 v204, v[134:137] offset:41472
	ds_write_b128 v204, v[130:133] offset:46080
	ds_write_b128 v204, v[138:141] offset:50688
	v_lshl_add_u64 v[130:131], v[178:179], 0, s[10:11]
	s_add_u32 s100, s10, 0x10000
	s_addc_u32 s101, s11, 0
	v_lshl_add_u64 v[132:133], v[178:179], 0, s[100:101]
	s_add_u32 s100, s100, 0x10000
	s_addc_u32 s101, s101, 0
	v_lshl_add_u64 v[134:135], v[178:179], 0, s[100:101]
	s_add_u32 s100, s100, 0x10000
	s_addc_u32 s101, s101, 0
	v_lshl_add_u64 v[136:137], v[178:179], 0, s[100:101]
	s_add_u32 s100, s100, 0x10000
	s_addc_u32 s101, s101, 0
	v_lshl_add_u64 v[138:139], v[178:179], 0, s[100:101]
	s_add_u32 s100, s100, 0x10000
	s_addc_u32 s101, s101, 0
	v_lshl_add_u64 v[140:141], v[178:179], 0, s[100:101]
	s_add_u32 s100, s100, 0x10000
	s_addc_u32 s101, s101, 0
	v_lshl_add_u64 v[142:143], v[178:179], 0, s[100:101]
	s_add_u32 s100, s100, 0x10000
	s_addc_u32 s101, s101, 0
	v_lshl_add_u64 v[144:145], v[178:179], 0, s[100:101]
	s_waitcnt lgkmcnt(0)
	s_barrier
	v_lshl_add_u64 v[224:225], v[180:181], 0, s[10:11]
	s_add_u32 s100, s10, 0x10000
	s_addc_u32 s101, s11, 0
	v_lshl_add_u64 v[226:227], v[180:181], 0, s[100:101]
	s_add_u32 s100, s100, 0x10000
	s_addc_u32 s101, s101, 0
	v_lshl_add_u64 v[228:229], v[180:181], 0, s[100:101]
	s_add_u32 s100, s100, 0x10000
	s_addc_u32 s101, s101, 0
	v_lshl_add_u64 v[230:231], v[180:181], 0, s[100:101]
	global_load_dwordx4 v[174:177], v[130:131], off
	global_load_dwordx4 v[170:173], v[132:133], off
	global_load_dwordx4 v[166:169], v[134:135], off
	global_load_dwordx4 v[162:165], v[136:137], off
	global_load_dwordx4 v[158:161], v[138:139], off
	global_load_dwordx4 v[154:157], v[140:141], off
	global_load_dwordx4 v[150:153], v[142:143], off
	global_load_dwordx4 v[146:149], v[144:145], off
	global_load_dwordx4 v[142:145], v[224:225], off
	global_load_dwordx4 v[134:137], v[226:227], off
	global_load_dwordx4 v[130:133], v[228:229], off
	global_load_dwordx4 v[138:141], v[230:231], off
	s_setprio 2
	ds_read_b128 v[224:227], v182
	ds_read_b128 v[228:231], v183 offset:36864
	ds_read_b128 v[232:235], v183 offset:41472
	ds_read_b128 v[184:187], v182 offset:4608
	ds_read_b128 v[236:239], v183 offset:46080
	ds_read_b128 v[240:243], v183 offset:50688
	s_waitcnt lgkmcnt(4)
	v_mfma_f32_32x32x16_bf16 v[114:129], v[224:227], v[228:231], v[114:129]
	ds_read_b128 v[188:191], v183 offset:36896
	ds_read_b128 v[192:195], v183 offset:41504
	s_waitcnt lgkmcnt(5)
	v_mfma_f32_32x32x16_bf16 v[82:97], v[224:227], v[232:235], v[82:97]
	ds_read_b128 v[196:199], v183 offset:46112
	ds_read_b128 v[200:203], v183 offset:50720
	s_waitcnt lgkmcnt(5)
	v_mfma_f32_32x32x16_bf16 v[98:113], v[224:227], v[236:239], v[98:113]
	s_waitcnt lgkmcnt(4)
	v_mfma_f32_32x32x16_bf16 v[66:81], v[224:227], v[240:243], v[66:81]
	ds_read_b128 v[224:227], v182 offset:32
	v_mfma_f32_32x32x16_bf16 v[50:65], v[184:187], v[228:231], v[50:65]
	v_mfma_f32_32x32x16_bf16 v[16:31], v[184:187], v[232:235], v[16:31]
	v_mfma_f32_32x32x16_bf16 v[34:49], v[184:187], v[236:239], v[34:49]
	v_mfma_f32_32x32x16_bf16 v[0:15], v[184:187], v[240:243], v[0:15]
	ds_read_b128 v[184:187], v182 offset:4640
	s_waitcnt lgkmcnt(1)
	v_mfma_f32_32x32x16_bf16 v[114:129], v[224:227], v[188:191], v[114:129]
	ds_read_b128 v[228:231], v183 offset:36928
	ds_read_b128 v[232:235], v183 offset:41536
	v_mfma_f32_32x32x16_bf16 v[82:97], v[224:227], v[192:195], v[82:97]
	ds_read_b128 v[236:239], v183 offset:46144
	ds_read_b128 v[240:243], v183 offset:50752
	v_mfma_f32_32x32x16_bf16 v[98:113], v[224:227], v[196:199], v[98:113]
	v_mfma_f32_32x32x16_bf16 v[66:81], v[224:227], v[200:203], v[66:81]
	ds_read_b128 v[224:227], v182 offset:64
	s_waitcnt lgkmcnt(5)
	v_mfma_f32_32x32x16_bf16 v[50:65], v[184:187], v[188:191], v[50:65]
	v_mfma_f32_32x32x16_bf16 v[16:31], v[184:187], v[192:195], v[16:31]
	v_mfma_f32_32x32x16_bf16 v[34:49], v[184:187], v[196:199], v[34:49]
	v_mfma_f32_32x32x16_bf16 v[0:15], v[184:187], v[200:203], v[0:15]
	ds_read_b128 v[184:187], v182 offset:4672
	s_waitcnt lgkmcnt(1)
	v_mfma_f32_32x32x16_bf16 v[114:129], v[224:227], v[228:231], v[114:129]
	ds_read_b128 v[188:191], v183 offset:36960
	ds_read_b128 v[192:195], v183 offset:41568
	v_mfma_f32_32x32x16_bf16 v[82:97], v[224:227], v[232:235], v[82:97]
	ds_read_b128 v[196:199], v183 offset:46176
	ds_read_b128 v[200:203], v183 offset:50784
	v_mfma_f32_32x32x16_bf16 v[98:113], v[224:227], v[236:239], v[98:113]
	v_mfma_f32_32x32x16_bf16 v[66:81], v[224:227], v[240:243], v[66:81]
	ds_read_b128 v[224:227], v182 offset:96
	s_waitcnt lgkmcnt(5)
	v_mfma_f32_32x32x16_bf16 v[50:65], v[184:187], v[228:231], v[50:65]
	v_mfma_f32_32x32x16_bf16 v[16:31], v[184:187], v[232:235], v[16:31]
	v_mfma_f32_32x32x16_bf16 v[34:49], v[184:187], v[236:239], v[34:49]
	v_mfma_f32_32x32x16_bf16 v[0:15], v[184:187], v[240:243], v[0:15]
	ds_read_b128 v[184:187], v182 offset:4704
	s_waitcnt lgkmcnt(1)
	v_mfma_f32_32x32x16_bf16 v[114:129], v[224:227], v[188:191], v[114:129]
	v_mfma_f32_32x32x16_bf16 v[82:97], v[224:227], v[192:195], v[82:97]
	v_mfma_f32_32x32x16_bf16 v[98:113], v[224:227], v[196:199], v[98:113]
	v_mfma_f32_32x32x16_bf16 v[66:81], v[224:227], v[200:203], v[66:81]
	s_waitcnt lgkmcnt(0)
	v_mfma_f32_32x32x16_bf16 v[50:65], v[184:187], v[188:191], v[50:65]
	v_mfma_f32_32x32x16_bf16 v[16:31], v[184:187], v[192:195], v[16:31]
	v_mfma_f32_32x32x16_bf16 v[34:49], v[184:187], v[196:199], v[34:49]
	v_mfma_f32_32x32x16_bf16 v[0:15], v[184:187], v[200:203], v[0:15]
	s_setprio 0
	s_mov_b32 s1, s3
	s_cmp_lg_u32 s3, 16
	s_cbranch_scc1 .LBB0_1018
	s_lshl_b32 s1, s2, 8
	s_bfe_i32 s2, s2, 0x10017
	s_lshr_b32 s2, s2, 19
	v_writelane_b32 v251, s12, 29
	s_add_i32 s2, s1, s2
	s_and_b32 s2, s2, 0xffffe000
	v_writelane_b32 v251, s13, 30
	s_ashr_i32 s12, s8, 8
	s_add_i32 s12, s12, s9
	s_sub_i32 s17, s1, s2
	s_cmp_gt_i32 s0, 15
	s_mov_b64 s[2:3], -1
	s_barrier
	s_cbranch_scc0 .LBB0_1025
	s_cmp_gt_u32 s0, 31
	s_cbranch_scc0 .LBB0_1022
	v_mov_b32_e32 v32, v206
	v_readlane_b32 s24, v249, 18
	s_waitcnt vmcnt(1)
	v_and_b32_e32 v130, 0xffffffc0, v32
	v_lshrrev_b32_e32 v131, 3, v32
	v_and_or_b32 v130, v131, 4, v130
	v_add_u32_e32 v132, s1, v130
	s_lshl_b32 s1, s0, 8
	v_readlane_b32 s26, v249, 20
	v_and_b32_e32 v32, 31, v32
	v_readlane_b32 s27, v249, 21
	s_add_u32 s2, s26, s1
	s_addc_u32 s3, s27, 0
	v_lshlrev_b32_e32 v32, 1, v32
	v_lshl_add_u64 v[130:131], s[2:3], 0, v[32:33]
	s_movk_i32 s2, 0xe000
	s_mov_b32 s3, -1
	v_lshl_add_u64 v[130:131], v[130:131], 0, s[2:3]
	v_ashrrev_i32_e32 v133, 31, v132
	s_movk_i32 s1, 0x7fff
	v_readlane_b32 s25, v249, 19
	s_waitcnt vmcnt(0)
	v_ashrrev_i32_e32 v133, 31, v132
	v_lshrrev_b32_e32 v134, 6, v206
	v_and_b32_e32 v135, 63, v206
	v_mul_u32_u24_e32 v158, 0x2200, v134
	v_lshrrev_b32_e32 v136, 5, v135
	v_and_b32_e32 v137, 31, v135
	v_mul_u32_u24_e32 v159, 0x440, v136
	v_lshl_add_u32 v159, v137, 1, v159
	v_add_u32_e32 v159, v159, v158
	v_lshrrev_b32_e32 v134, 4, v135
	v_and_b32_e32 v135, 15, v135
	v_mul_u32_u24_e32 v160, 0x110, v134
	v_lshl_add_u32 v160, v135, 4, v160
	v_add_u32_e32 v160, v160, v158
	v_lshlrev_b32_e32 v136, 2, v136
	v_sub_u32_e32 v138, v132, v136
	v_add_u32_e32 v138, v138, v134
	v_ashrrev_i32_e32 v139, 31, v138
	v_lshlrev_b64 v[138:139], 12, v[138:139]
	v_lshlrev_b32_e32 v135, 4, v135
	v_lshlrev_b32_e32 v137, 1, v137
	v_sub_u32_e32 v140, v135, v137
	v_ashrrev_i32_e32 v141, 31, v140
	v_lshl_add_u64 v[162:163], v[130:131], 0, v[138:139]
	v_lshl_add_u64 v[162:163], v[162:163], 0, v[140:141]
	v_mul_f32_e32 v134, 0xbfb8aa3b, v114
	v_mul_f32_e32 v135, 0xbfb8aa3b, v115
	v_mul_f32_e32 v146, 0xbfb8aa3b, v82
	v_mul_f32_e32 v147, 0xbfb8aa3b, v83
	v_exp_f32_e32 v134, v134
	v_exp_f32_e32 v135, v135
	v_exp_f32_e32 v146, v146
	v_exp_f32_e32 v147, v147
	v_pk_add_f32 v[134:135], v[134:135], 1.0 op_sel_hi:[1,0]
	v_pk_add_f32 v[146:147], v[146:147], 1.0 op_sel_hi:[1,0]
	v_div_scale_f32 v136, vcc, v134, v134, v114
	v_div_scale_f32 v137, vcc, v135, v135, v115
	v_div_scale_f32 v148, vcc, v146, v146, v82
	v_div_scale_f32 v149, vcc, v147, v147, v83
	v_rcp_f32_e32 v138, v136
	v_rcp_f32_e32 v139, v137
	v_rcp_f32_e32 v150, v148
	v_rcp_f32_e32 v151, v149
	v_pk_fma_f32 v[140:141], v[136:137], v[138:139], 1.0 op_sel_hi:[1,1,0] neg_lo:[1,0,0] neg_hi:[1,0,0]
	v_pk_fma_f32 v[152:153], v[148:149], v[150:151], 1.0 op_sel_hi:[1,1,0] neg_lo:[1,0,0] neg_hi:[1,0,0]
	v_pk_fma_f32 v[138:139], v[140:141], v[138:139], v[138:139]
	v_pk_fma_f32 v[150:151], v[152:153], v[150:151], v[150:151]
	v_div_scale_f32 v142, s[28:29], v114, v134, v114
	v_div_scale_f32 v143, s[30:31], v115, v135, v115
	v_div_scale_f32 v154, s[2:3], v82, v146, v82
	v_div_scale_f32 v155, s[100:101], v83, v147, v83
	v_pk_mul_f32 v[144:145], v[142:143], v[138:139]
	v_pk_mul_f32 v[156:157], v[154:155], v[150:151]
	v_pk_fma_f32 v[140:141], v[136:137], v[144:145], v[142:143] neg_lo:[1,0,0] neg_hi:[1,0,0]
	v_pk_fma_f32 v[152:153], v[148:149], v[156:157], v[154:155] neg_lo:[1,0,0] neg_hi:[1,0,0]
	v_pk_fma_f32 v[144:145], v[140:141], v[138:139], v[144:145]
	v_pk_fma_f32 v[156:157], v[152:153], v[150:151], v[156:157]
	v_pk_fma_f32 v[136:137], v[136:137], v[144:145], v[142:143] neg_lo:[1,0,0] neg_hi:[1,0,0]
	v_pk_fma_f32 v[148:149], v[148:149], v[156:157], v[154:155] neg_lo:[1,0,0] neg_hi:[1,0,0]
	s_mov_b64 vcc, s[28:29]
	v_div_fmas_f32 v136, v136, v138, v144
	s_mov_b64 vcc, s[30:31]
	v_div_fmas_f32 v137, v137, v139, v145
	s_mov_b64 vcc, s[2:3]
	v_div_fmas_f32 v148, v148, v150, v156
	s_mov_b64 vcc, s[100:101]
	v_div_fmas_f32 v149, v149, v151, v157
	v_div_fixup_f32 v134, v136, v134, v114
	v_div_fixup_f32 v135, v137, v135, v115
	v_div_fixup_f32 v146, v148, v146, v82
	v_div_fixup_f32 v147, v149, v147, v83
	v_cvt_pk_bf16_f32 v136, v134, v135
	v_cvt_pk_bf16_f32 v148, v146, v147
	ds_write_b16 v159, v136 offset:0
	ds_write_b16_d16_hi v159, v136 offset:272
	ds_write_b16 v159, v148 offset:64
	ds_write_b16_d16_hi v159, v148 offset:336
	v_mul_f32_e32 v134, 0xbfb8aa3b, v98
	v_mul_f32_e32 v135, 0xbfb8aa3b, v99
	v_mul_f32_e32 v146, 0xbfb8aa3b, v66
	v_mul_f32_e32 v147, 0xbfb8aa3b, v67
	v_exp_f32_e32 v134, v134
	v_exp_f32_e32 v135, v135
	v_exp_f32_e32 v146, v146
	v_exp_f32_e32 v147, v147
	v_pk_add_f32 v[134:135], v[134:135], 1.0 op_sel_hi:[1,0]
	v_pk_add_f32 v[146:147], v[146:147], 1.0 op_sel_hi:[1,0]
	v_div_scale_f32 v136, vcc, v134, v134, v98
	v_div_scale_f32 v137, vcc, v135, v135, v99
	v_div_scale_f32 v148, vcc, v146, v146, v66
	v_div_scale_f32 v149, vcc, v147, v147, v67
	v_rcp_f32_e32 v138, v136
	v_rcp_f32_e32 v139, v137
	v_rcp_f32_e32 v150, v148
	v_rcp_f32_e32 v151, v149
	v_pk_fma_f32 v[140:141], v[136:137], v[138:139], 1.0 op_sel_hi:[1,1,0] neg_lo:[1,0,0] neg_hi:[1,0,0]
	v_pk_fma_f32 v[152:153], v[148:149], v[150:151], 1.0 op_sel_hi:[1,1,0] neg_lo:[1,0,0] neg_hi:[1,0,0]
	v_pk_fma_f32 v[138:139], v[140:141], v[138:139], v[138:139]
	v_pk_fma_f32 v[150:151], v[152:153], v[150:151], v[150:151]
	v_div_scale_f32 v142, s[28:29], v98, v134, v98
	v_div_scale_f32 v143, s[30:31], v99, v135, v99
	v_div_scale_f32 v154, s[2:3], v66, v146, v66
	v_div_scale_f32 v155, s[100:101], v67, v147, v67
	v_pk_mul_f32 v[144:145], v[142:143], v[138:139]
	v_pk_mul_f32 v[156:157], v[154:155], v[150:151]
	v_pk_fma_f32 v[140:141], v[136:137], v[144:145], v[142:143] neg_lo:[1,0,0] neg_hi:[1,0,0]
	v_pk_fma_f32 v[152:153], v[148:149], v[156:157], v[154:155] neg_lo:[1,0,0] neg_hi:[1,0,0]
	v_pk_fma_f32 v[144:145], v[140:141], v[138:139], v[144:145]
	v_pk_fma_f32 v[156:157], v[152:153], v[150:151], v[156:157]
	v_pk_fma_f32 v[136:137], v[136:137], v[144:145], v[142:143] neg_lo:[1,0,0] neg_hi:[1,0,0]
	v_pk_fma_f32 v[148:149], v[148:149], v[156:157], v[154:155] neg_lo:[1,0,0] neg_hi:[1,0,0]
	s_mov_b64 vcc, s[28:29]
	v_div_fmas_f32 v136, v136, v138, v144
	s_mov_b64 vcc, s[30:31]
	v_div_fmas_f32 v137, v137, v139, v145
	s_mov_b64 vcc, s[2:3]
	v_div_fmas_f32 v148, v148, v150, v156
	s_mov_b64 vcc, s[100:101]
	v_div_fmas_f32 v149, v149, v151, v157
	v_div_fixup_f32 v134, v136, v134, v98
	v_div_fixup_f32 v135, v137, v135, v99
	v_div_fixup_f32 v146, v148, v146, v66
	v_div_fixup_f32 v147, v149, v147, v67
	v_cvt_pk_bf16_f32 v136, v134, v135
	v_cvt_pk_bf16_f32 v148, v146, v147
	ds_write_b16 v159, v136 offset:128
	ds_write_b16_d16_hi v159, v136 offset:400
	ds_write_b16 v159, v148 offset:192
	ds_write_b16_d16_hi v159, v148 offset:464
	v_mul_f32_e32 v134, 0xbfb8aa3b, v116
	v_mul_f32_e32 v135, 0xbfb8aa3b, v117
	v_mul_f32_e32 v146, 0xbfb8aa3b, v84
	v_mul_f32_e32 v147, 0xbfb8aa3b, v85
	v_exp_f32_e32 v134, v134
	v_exp_f32_e32 v135, v135
	v_exp_f32_e32 v146, v146
	v_exp_f32_e32 v147, v147
	v_pk_add_f32 v[134:135], v[134:135], 1.0 op_sel_hi:[1,0]
	v_pk_add_f32 v[146:147], v[146:147], 1.0 op_sel_hi:[1,0]
	v_div_scale_f32 v136, vcc, v134, v134, v116
	v_div_scale_f32 v137, vcc, v135, v135, v117
	v_div_scale_f32 v148, vcc, v146, v146, v84
	v_div_scale_f32 v149, vcc, v147, v147, v85
	v_rcp_f32_e32 v138, v136
	v_rcp_f32_e32 v139, v137
	v_rcp_f32_e32 v150, v148
	v_rcp_f32_e32 v151, v149
	v_pk_fma_f32 v[140:141], v[136:137], v[138:139], 1.0 op_sel_hi:[1,1,0] neg_lo:[1,0,0] neg_hi:[1,0,0]
	v_pk_fma_f32 v[152:153], v[148:149], v[150:151], 1.0 op_sel_hi:[1,1,0] neg_lo:[1,0,0] neg_hi:[1,0,0]
	v_pk_fma_f32 v[138:139], v[140:141], v[138:139], v[138:139]
	v_pk_fma_f32 v[150:151], v[152:153], v[150:151], v[150:151]
	v_div_scale_f32 v142, s[28:29], v116, v134, v116
	v_div_scale_f32 v143, s[30:31], v117, v135, v117
	v_div_scale_f32 v154, s[2:3], v84, v146, v84
	v_div_scale_f32 v155, s[100:101], v85, v147, v85
	v_pk_mul_f32 v[144:145], v[142:143], v[138:139]
	v_pk_mul_f32 v[156:157], v[154:155], v[150:151]
	v_pk_fma_f32 v[140:141], v[136:137], v[144:145], v[142:143] neg_lo:[1,0,0] neg_hi:[1,0,0]
	v_pk_fma_f32 v[152:153], v[148:149], v[156:157], v[154:155] neg_lo:[1,0,0] neg_hi:[1,0,0]
	v_pk_fma_f32 v[144:145], v[140:141], v[138:139], v[144:145]
	v_pk_fma_f32 v[156:157], v[152:153], v[150:151], v[156:157]
	v_pk_fma_f32 v[136:137], v[136:137], v[144:145], v[142:143] neg_lo:[1,0,0] neg_hi:[1,0,0]
	v_pk_fma_f32 v[148:149], v[148:149], v[156:157], v[154:155] neg_lo:[1,0,0] neg_hi:[1,0,0]
	s_mov_b64 vcc, s[28:29]
	v_div_fmas_f32 v136, v136, v138, v144
	s_mov_b64 vcc, s[30:31]
	v_div_fmas_f32 v137, v137, v139, v145
	s_mov_b64 vcc, s[2:3]
	v_div_fmas_f32 v148, v148, v150, v156
	s_mov_b64 vcc, s[100:101]
	v_div_fmas_f32 v149, v149, v151, v157
	v_div_fixup_f32 v134, v136, v134, v116
	v_div_fixup_f32 v135, v137, v135, v117
	v_div_fixup_f32 v146, v148, v146, v84
	v_div_fixup_f32 v147, v149, v147, v85
	v_cvt_pk_bf16_f32 v136, v134, v135
	v_cvt_pk_bf16_f32 v148, v146, v147
	ds_write_b16 v159, v136 offset:544
	ds_write_b16_d16_hi v159, v136 offset:816
	ds_write_b16 v159, v148 offset:608
	ds_write_b16_d16_hi v159, v148 offset:880
	v_mul_f32_e32 v134, 0xbfb8aa3b, v100
	v_mul_f32_e32 v135, 0xbfb8aa3b, v101
	v_mul_f32_e32 v146, 0xbfb8aa3b, v68
	v_mul_f32_e32 v147, 0xbfb8aa3b, v69
	v_exp_f32_e32 v134, v134
	v_exp_f32_e32 v135, v135
	v_exp_f32_e32 v146, v146
	v_exp_f32_e32 v147, v147
	v_pk_add_f32 v[134:135], v[134:135], 1.0 op_sel_hi:[1,0]
	v_pk_add_f32 v[146:147], v[146:147], 1.0 op_sel_hi:[1,0]
	v_div_scale_f32 v136, vcc, v134, v134, v100
	v_div_scale_f32 v137, vcc, v135, v135, v101
	v_div_scale_f32 v148, vcc, v146, v146, v68
	v_div_scale_f32 v149, vcc, v147, v147, v69
	v_rcp_f32_e32 v138, v136
	v_rcp_f32_e32 v139, v137
	v_rcp_f32_e32 v150, v148
	v_rcp_f32_e32 v151, v149
	v_pk_fma_f32 v[140:141], v[136:137], v[138:139], 1.0 op_sel_hi:[1,1,0] neg_lo:[1,0,0] neg_hi:[1,0,0]
	v_pk_fma_f32 v[152:153], v[148:149], v[150:151], 1.0 op_sel_hi:[1,1,0] neg_lo:[1,0,0] neg_hi:[1,0,0]
	v_pk_fma_f32 v[138:139], v[140:141], v[138:139], v[138:139]
	v_pk_fma_f32 v[150:151], v[152:153], v[150:151], v[150:151]
	v_div_scale_f32 v142, s[28:29], v100, v134, v100
	v_div_scale_f32 v143, s[30:31], v101, v135, v101
	v_div_scale_f32 v154, s[2:3], v68, v146, v68
	v_div_scale_f32 v155, s[100:101], v69, v147, v69
	v_pk_mul_f32 v[144:145], v[142:143], v[138:139]
	v_pk_mul_f32 v[156:157], v[154:155], v[150:151]
	v_pk_fma_f32 v[140:141], v[136:137], v[144:145], v[142:143] neg_lo:[1,0,0] neg_hi:[1,0,0]
	v_pk_fma_f32 v[152:153], v[148:149], v[156:157], v[154:155] neg_lo:[1,0,0] neg_hi:[1,0,0]
	v_pk_fma_f32 v[144:145], v[140:141], v[138:139], v[144:145]
	v_pk_fma_f32 v[156:157], v[152:153], v[150:151], v[156:157]
	v_pk_fma_f32 v[136:137], v[136:137], v[144:145], v[142:143] neg_lo:[1,0,0] neg_hi:[1,0,0]
	v_pk_fma_f32 v[148:149], v[148:149], v[156:157], v[154:155] neg_lo:[1,0,0] neg_hi:[1,0,0]
	s_mov_b64 vcc, s[28:29]
	v_div_fmas_f32 v136, v136, v138, v144
	s_mov_b64 vcc, s[30:31]
	v_div_fmas_f32 v137, v137, v139, v145
	s_mov_b64 vcc, s[2:3]
	v_div_fmas_f32 v148, v148, v150, v156
	s_mov_b64 vcc, s[100:101]
	v_div_fmas_f32 v149, v149, v151, v157
	v_div_fixup_f32 v134, v136, v134, v100
	v_div_fixup_f32 v135, v137, v135, v101
	v_div_fixup_f32 v146, v148, v146, v68
	v_div_fixup_f32 v147, v149, v147, v69
	v_cvt_pk_bf16_f32 v136, v134, v135
	v_cvt_pk_bf16_f32 v148, v146, v147
	ds_write_b16 v159, v136 offset:672
	ds_write_b16_d16_hi v159, v136 offset:944
	ds_write_b16 v159, v148 offset:736
	ds_write_b16_d16_hi v159, v148 offset:1008
	v_mul_f32_e32 v134, 0xbfb8aa3b, v118
	v_mul_f32_e32 v135, 0xbfb8aa3b, v119
	v_mul_f32_e32 v146, 0xbfb8aa3b, v86
	v_mul_f32_e32 v147, 0xbfb8aa3b, v87
	v_exp_f32_e32 v134, v134
	v_exp_f32_e32 v135, v135
	v_exp_f32_e32 v146, v146
	v_exp_f32_e32 v147, v147
	v_pk_add_f32 v[134:135], v[134:135], 1.0 op_sel_hi:[1,0]
	v_pk_add_f32 v[146:147], v[146:147], 1.0 op_sel_hi:[1,0]
	v_div_scale_f32 v136, vcc, v134, v134, v118
	v_div_scale_f32 v137, vcc, v135, v135, v119
	v_div_scale_f32 v148, vcc, v146, v146, v86
	v_div_scale_f32 v149, vcc, v147, v147, v87
	v_rcp_f32_e32 v138, v136
	v_rcp_f32_e32 v139, v137
	v_rcp_f32_e32 v150, v148
	v_rcp_f32_e32 v151, v149
	v_pk_fma_f32 v[140:141], v[136:137], v[138:139], 1.0 op_sel_hi:[1,1,0] neg_lo:[1,0,0] neg_hi:[1,0,0]
	v_pk_fma_f32 v[152:153], v[148:149], v[150:151], 1.0 op_sel_hi:[1,1,0] neg_lo:[1,0,0] neg_hi:[1,0,0]
	v_pk_fma_f32 v[138:139], v[140:141], v[138:139], v[138:139]
	v_pk_fma_f32 v[150:151], v[152:153], v[150:151], v[150:151]
	v_div_scale_f32 v142, s[28:29], v118, v134, v118
	v_div_scale_f32 v143, s[30:31], v119, v135, v119
	v_div_scale_f32 v154, s[2:3], v86, v146, v86
	v_div_scale_f32 v155, s[100:101], v87, v147, v87
	v_pk_mul_f32 v[144:145], v[142:143], v[138:139]
	v_pk_mul_f32 v[156:157], v[154:155], v[150:151]
	v_pk_fma_f32 v[140:141], v[136:137], v[144:145], v[142:143] neg_lo:[1,0,0] neg_hi:[1,0,0]
	v_pk_fma_f32 v[152:153], v[148:149], v[156:157], v[154:155] neg_lo:[1,0,0] neg_hi:[1,0,0]
	v_pk_fma_f32 v[144:145], v[140:141], v[138:139], v[144:145]
	v_pk_fma_f32 v[156:157], v[152:153], v[150:151], v[156:157]
	v_pk_fma_f32 v[136:137], v[136:137], v[144:145], v[142:143] neg_lo:[1,0,0] neg_hi:[1,0,0]
	v_pk_fma_f32 v[148:149], v[148:149], v[156:157], v[154:155] neg_lo:[1,0,0] neg_hi:[1,0,0]
	s_mov_b64 vcc, s[28:29]
	v_div_fmas_f32 v136, v136, v138, v144
	s_mov_b64 vcc, s[30:31]
	v_div_fmas_f32 v137, v137, v139, v145
	s_mov_b64 vcc, s[2:3]
	v_div_fmas_f32 v148, v148, v150, v156
	s_mov_b64 vcc, s[100:101]
	v_div_fmas_f32 v149, v149, v151, v157
	v_div_fixup_f32 v134, v136, v134, v118
	v_div_fixup_f32 v135, v137, v135, v119
	v_div_fixup_f32 v146, v148, v146, v86
	v_div_fixup_f32 v147, v149, v147, v87
	v_cvt_pk_bf16_f32 v136, v134, v135
	v_cvt_pk_bf16_f32 v148, v146, v147
	ds_write_b16 v159, v136 offset:2176
	ds_write_b16_d16_hi v159, v136 offset:2448
	ds_write_b16 v159, v148 offset:2240
	ds_write_b16_d16_hi v159, v148 offset:2512
	v_mul_f32_e32 v134, 0xbfb8aa3b, v102
	v_mul_f32_e32 v135, 0xbfb8aa3b, v103
	v_mul_f32_e32 v146, 0xbfb8aa3b, v70
	v_mul_f32_e32 v147, 0xbfb8aa3b, v71
	v_exp_f32_e32 v134, v134
	v_exp_f32_e32 v135, v135
	v_exp_f32_e32 v146, v146
	v_exp_f32_e32 v147, v147
	v_pk_add_f32 v[134:135], v[134:135], 1.0 op_sel_hi:[1,0]
	v_pk_add_f32 v[146:147], v[146:147], 1.0 op_sel_hi:[1,0]
	v_div_scale_f32 v136, vcc, v134, v134, v102
	v_div_scale_f32 v137, vcc, v135, v135, v103
	v_div_scale_f32 v148, vcc, v146, v146, v70
	v_div_scale_f32 v149, vcc, v147, v147, v71
	v_rcp_f32_e32 v138, v136
	v_rcp_f32_e32 v139, v137
	v_rcp_f32_e32 v150, v148
	v_rcp_f32_e32 v151, v149
	v_pk_fma_f32 v[140:141], v[136:137], v[138:139], 1.0 op_sel_hi:[1,1,0] neg_lo:[1,0,0] neg_hi:[1,0,0]
	v_pk_fma_f32 v[152:153], v[148:149], v[150:151], 1.0 op_sel_hi:[1,1,0] neg_lo:[1,0,0] neg_hi:[1,0,0]
	v_pk_fma_f32 v[138:139], v[140:141], v[138:139], v[138:139]
	v_pk_fma_f32 v[150:151], v[152:153], v[150:151], v[150:151]
	v_div_scale_f32 v142, s[28:29], v102, v134, v102
	v_div_scale_f32 v143, s[30:31], v103, v135, v103
	v_div_scale_f32 v154, s[2:3], v70, v146, v70
	v_div_scale_f32 v155, s[100:101], v71, v147, v71
	v_pk_mul_f32 v[144:145], v[142:143], v[138:139]
	v_pk_mul_f32 v[156:157], v[154:155], v[150:151]
	v_pk_fma_f32 v[140:141], v[136:137], v[144:145], v[142:143] neg_lo:[1,0,0] neg_hi:[1,0,0]
	v_pk_fma_f32 v[152:153], v[148:149], v[156:157], v[154:155] neg_lo:[1,0,0] neg_hi:[1,0,0]
	v_pk_fma_f32 v[144:145], v[140:141], v[138:139], v[144:145]
	v_pk_fma_f32 v[156:157], v[152:153], v[150:151], v[156:157]
	v_pk_fma_f32 v[136:137], v[136:137], v[144:145], v[142:143] neg_lo:[1,0,0] neg_hi:[1,0,0]
	v_pk_fma_f32 v[148:149], v[148:149], v[156:157], v[154:155] neg_lo:[1,0,0] neg_hi:[1,0,0]
	s_mov_b64 vcc, s[28:29]
	v_div_fmas_f32 v136, v136, v138, v144
	s_mov_b64 vcc, s[30:31]
	v_div_fmas_f32 v137, v137, v139, v145
	s_mov_b64 vcc, s[2:3]
	v_div_fmas_f32 v148, v148, v150, v156
	s_mov_b64 vcc, s[100:101]
	v_div_fmas_f32 v149, v149, v151, v157
	v_div_fixup_f32 v134, v136, v134, v102
	v_div_fixup_f32 v135, v137, v135, v103
	v_div_fixup_f32 v146, v148, v146, v70
	v_div_fixup_f32 v147, v149, v147, v71
	v_cvt_pk_bf16_f32 v136, v134, v135
	v_cvt_pk_bf16_f32 v148, v146, v147
	ds_write_b16 v159, v136 offset:2304
	ds_write_b16_d16_hi v159, v136 offset:2576
	ds_write_b16 v159, v148 offset:2368
	ds_write_b16_d16_hi v159, v148 offset:2640
	v_mul_f32_e32 v134, 0xbfb8aa3b, v120
	v_mul_f32_e32 v135, 0xbfb8aa3b, v121
	v_mul_f32_e32 v146, 0xbfb8aa3b, v88
	v_mul_f32_e32 v147, 0xbfb8aa3b, v89
	v_exp_f32_e32 v134, v134
	v_exp_f32_e32 v135, v135
	v_exp_f32_e32 v146, v146
	v_exp_f32_e32 v147, v147
	v_pk_add_f32 v[134:135], v[134:135], 1.0 op_sel_hi:[1,0]
	v_pk_add_f32 v[146:147], v[146:147], 1.0 op_sel_hi:[1,0]
	v_div_scale_f32 v136, vcc, v134, v134, v120
	v_div_scale_f32 v137, vcc, v135, v135, v121
	v_div_scale_f32 v148, vcc, v146, v146, v88
	v_div_scale_f32 v149, vcc, v147, v147, v89
	v_rcp_f32_e32 v138, v136
	v_rcp_f32_e32 v139, v137
	v_rcp_f32_e32 v150, v148
	v_rcp_f32_e32 v151, v149
	v_pk_fma_f32 v[140:141], v[136:137], v[138:139], 1.0 op_sel_hi:[1,1,0] neg_lo:[1,0,0] neg_hi:[1,0,0]
	v_pk_fma_f32 v[152:153], v[148:149], v[150:151], 1.0 op_sel_hi:[1,1,0] neg_lo:[1,0,0] neg_hi:[1,0,0]
	v_pk_fma_f32 v[138:139], v[140:141], v[138:139], v[138:139]
	v_pk_fma_f32 v[150:151], v[152:153], v[150:151], v[150:151]
	v_div_scale_f32 v142, s[28:29], v120, v134, v120
	v_div_scale_f32 v143, s[30:31], v121, v135, v121
	v_div_scale_f32 v154, s[2:3], v88, v146, v88
	v_div_scale_f32 v155, s[100:101], v89, v147, v89
	v_pk_mul_f32 v[144:145], v[142:143], v[138:139]
	v_pk_mul_f32 v[156:157], v[154:155], v[150:151]
	v_pk_fma_f32 v[140:141], v[136:137], v[144:145], v[142:143] neg_lo:[1,0,0] neg_hi:[1,0,0]
	v_pk_fma_f32 v[152:153], v[148:149], v[156:157], v[154:155] neg_lo:[1,0,0] neg_hi:[1,0,0]
	v_pk_fma_f32 v[144:145], v[140:141], v[138:139], v[144:145]
	v_pk_fma_f32 v[156:157], v[152:153], v[150:151], v[156:157]
	v_pk_fma_f32 v[136:137], v[136:137], v[144:145], v[142:143] neg_lo:[1,0,0] neg_hi:[1,0,0]
	v_pk_fma_f32 v[148:149], v[148:149], v[156:157], v[154:155] neg_lo:[1,0,0] neg_hi:[1,0,0]
	s_mov_b64 vcc, s[28:29]
	v_div_fmas_f32 v136, v136, v138, v144
	s_mov_b64 vcc, s[30:31]
	v_div_fmas_f32 v137, v137, v139, v145
	s_mov_b64 vcc, s[2:3]
	v_div_fmas_f32 v148, v148, v150, v156
	s_mov_b64 vcc, s[100:101]
	v_div_fmas_f32 v149, v149, v151, v157
	v_div_fixup_f32 v134, v136, v134, v120
	v_div_fixup_f32 v135, v137, v135, v121
	v_div_fixup_f32 v146, v148, v146, v88
	v_div_fixup_f32 v147, v149, v147, v89
	v_cvt_pk_bf16_f32 v136, v134, v135
	v_cvt_pk_bf16_f32 v148, v146, v147
	ds_write_b16 v159, v136 offset:2720
	ds_write_b16_d16_hi v159, v136 offset:2992
	ds_write_b16 v159, v148 offset:2784
	ds_write_b16_d16_hi v159, v148 offset:3056
	v_mul_f32_e32 v134, 0xbfb8aa3b, v104
	v_mul_f32_e32 v135, 0xbfb8aa3b, v105
	v_mul_f32_e32 v146, 0xbfb8aa3b, v72
	v_mul_f32_e32 v147, 0xbfb8aa3b, v73
	v_exp_f32_e32 v134, v134
	v_exp_f32_e32 v135, v135
	v_exp_f32_e32 v146, v146
	v_exp_f32_e32 v147, v147
	v_pk_add_f32 v[134:135], v[134:135], 1.0 op_sel_hi:[1,0]
	v_pk_add_f32 v[146:147], v[146:147], 1.0 op_sel_hi:[1,0]
	v_div_scale_f32 v136, vcc, v134, v134, v104
	v_div_scale_f32 v137, vcc, v135, v135, v105
	v_div_scale_f32 v148, vcc, v146, v146, v72
	v_div_scale_f32 v149, vcc, v147, v147, v73
	v_rcp_f32_e32 v138, v136
	v_rcp_f32_e32 v139, v137
	v_rcp_f32_e32 v150, v148
	v_rcp_f32_e32 v151, v149
	v_pk_fma_f32 v[140:141], v[136:137], v[138:139], 1.0 op_sel_hi:[1,1,0] neg_lo:[1,0,0] neg_hi:[1,0,0]
	v_pk_fma_f32 v[152:153], v[148:149], v[150:151], 1.0 op_sel_hi:[1,1,0] neg_lo:[1,0,0] neg_hi:[1,0,0]
	v_pk_fma_f32 v[138:139], v[140:141], v[138:139], v[138:139]
	v_pk_fma_f32 v[150:151], v[152:153], v[150:151], v[150:151]
	v_div_scale_f32 v142, s[28:29], v104, v134, v104
	v_div_scale_f32 v143, s[30:31], v105, v135, v105
	v_div_scale_f32 v154, s[2:3], v72, v146, v72
	v_div_scale_f32 v155, s[100:101], v73, v147, v73
	v_pk_mul_f32 v[144:145], v[142:143], v[138:139]
	v_pk_mul_f32 v[156:157], v[154:155], v[150:151]
	v_pk_fma_f32 v[140:141], v[136:137], v[144:145], v[142:143] neg_lo:[1,0,0] neg_hi:[1,0,0]
	v_pk_fma_f32 v[152:153], v[148:149], v[156:157], v[154:155] neg_lo:[1,0,0] neg_hi:[1,0,0]
	v_pk_fma_f32 v[144:145], v[140:141], v[138:139], v[144:145]
	v_pk_fma_f32 v[156:157], v[152:153], v[150:151], v[156:157]
	v_pk_fma_f32 v[136:137], v[136:137], v[144:145], v[142:143] neg_lo:[1,0,0] neg_hi:[1,0,0]
	v_pk_fma_f32 v[148:149], v[148:149], v[156:157], v[154:155] neg_lo:[1,0,0] neg_hi:[1,0,0]
	s_mov_b64 vcc, s[28:29]
	v_div_fmas_f32 v136, v136, v138, v144
	s_mov_b64 vcc, s[30:31]
	v_div_fmas_f32 v137, v137, v139, v145
	s_mov_b64 vcc, s[2:3]
	v_div_fmas_f32 v148, v148, v150, v156
	s_mov_b64 vcc, s[100:101]
	v_div_fmas_f32 v149, v149, v151, v157
	v_div_fixup_f32 v134, v136, v134, v104
	v_div_fixup_f32 v135, v137, v135, v105
	v_div_fixup_f32 v146, v148, v146, v72
	v_div_fixup_f32 v147, v149, v147, v73
	v_cvt_pk_bf16_f32 v136, v134, v135
	v_cvt_pk_bf16_f32 v148, v146, v147
	ds_write_b16 v159, v136 offset:2848
	ds_write_b16_d16_hi v159, v136 offset:3120
	ds_write_b16 v159, v148 offset:2912
	ds_write_b16_d16_hi v159, v148 offset:3184
	v_mul_f32_e32 v134, 0xbfb8aa3b, v122
	v_mul_f32_e32 v135, 0xbfb8aa3b, v123
	v_mul_f32_e32 v146, 0xbfb8aa3b, v90
	v_mul_f32_e32 v147, 0xbfb8aa3b, v91
	v_exp_f32_e32 v134, v134
	v_exp_f32_e32 v135, v135
	v_exp_f32_e32 v146, v146
	v_exp_f32_e32 v147, v147
	v_pk_add_f32 v[134:135], v[134:135], 1.0 op_sel_hi:[1,0]
	v_pk_add_f32 v[146:147], v[146:147], 1.0 op_sel_hi:[1,0]
	v_div_scale_f32 v136, vcc, v134, v134, v122
	v_div_scale_f32 v137, vcc, v135, v135, v123
	v_div_scale_f32 v148, vcc, v146, v146, v90
	v_div_scale_f32 v149, vcc, v147, v147, v91
	v_rcp_f32_e32 v138, v136
	v_rcp_f32_e32 v139, v137
	v_rcp_f32_e32 v150, v148
	v_rcp_f32_e32 v151, v149
	v_pk_fma_f32 v[140:141], v[136:137], v[138:139], 1.0 op_sel_hi:[1,1,0] neg_lo:[1,0,0] neg_hi:[1,0,0]
	v_pk_fma_f32 v[152:153], v[148:149], v[150:151], 1.0 op_sel_hi:[1,1,0] neg_lo:[1,0,0] neg_hi:[1,0,0]
	v_pk_fma_f32 v[138:139], v[140:141], v[138:139], v[138:139]
	v_pk_fma_f32 v[150:151], v[152:153], v[150:151], v[150:151]
	v_div_scale_f32 v142, s[28:29], v122, v134, v122
	v_div_scale_f32 v143, s[30:31], v123, v135, v123
	v_div_scale_f32 v154, s[2:3], v90, v146, v90
	v_div_scale_f32 v155, s[100:101], v91, v147, v91
	v_pk_mul_f32 v[144:145], v[142:143], v[138:139]
	v_pk_mul_f32 v[156:157], v[154:155], v[150:151]
	v_pk_fma_f32 v[140:141], v[136:137], v[144:145], v[142:143] neg_lo:[1,0,0] neg_hi:[1,0,0]
	v_pk_fma_f32 v[152:153], v[148:149], v[156:157], v[154:155] neg_lo:[1,0,0] neg_hi:[1,0,0]
	v_pk_fma_f32 v[144:145], v[140:141], v[138:139], v[144:145]
	v_pk_fma_f32 v[156:157], v[152:153], v[150:151], v[156:157]
	v_pk_fma_f32 v[136:137], v[136:137], v[144:145], v[142:143] neg_lo:[1,0,0] neg_hi:[1,0,0]
	v_pk_fma_f32 v[148:149], v[148:149], v[156:157], v[154:155] neg_lo:[1,0,0] neg_hi:[1,0,0]
	s_mov_b64 vcc, s[28:29]
	v_div_fmas_f32 v136, v136, v138, v144
	s_mov_b64 vcc, s[30:31]
	v_div_fmas_f32 v137, v137, v139, v145
	s_mov_b64 vcc, s[2:3]
	v_div_fmas_f32 v148, v148, v150, v156
	s_mov_b64 vcc, s[100:101]
	v_div_fmas_f32 v149, v149, v151, v157
	v_div_fixup_f32 v134, v136, v134, v122
	v_div_fixup_f32 v135, v137, v135, v123
	v_div_fixup_f32 v146, v148, v146, v90
	v_div_fixup_f32 v147, v149, v147, v91
	v_cvt_pk_bf16_f32 v136, v134, v135
	v_cvt_pk_bf16_f32 v148, v146, v147
	ds_write_b16 v159, v136 offset:4352
	ds_write_b16_d16_hi v159, v136 offset:4624
	ds_write_b16 v159, v148 offset:4416
	ds_write_b16_d16_hi v159, v148 offset:4688
	v_mul_f32_e32 v134, 0xbfb8aa3b, v106
	v_mul_f32_e32 v135, 0xbfb8aa3b, v107
	v_mul_f32_e32 v146, 0xbfb8aa3b, v74
	v_mul_f32_e32 v147, 0xbfb8aa3b, v75
	v_exp_f32_e32 v134, v134
	v_exp_f32_e32 v135, v135
	v_exp_f32_e32 v146, v146
	v_exp_f32_e32 v147, v147
	v_pk_add_f32 v[134:135], v[134:135], 1.0 op_sel_hi:[1,0]
	v_pk_add_f32 v[146:147], v[146:147], 1.0 op_sel_hi:[1,0]
	v_div_scale_f32 v136, vcc, v134, v134, v106
	v_div_scale_f32 v137, vcc, v135, v135, v107
	v_div_scale_f32 v148, vcc, v146, v146, v74
	v_div_scale_f32 v149, vcc, v147, v147, v75
	v_rcp_f32_e32 v138, v136
	v_rcp_f32_e32 v139, v137
	v_rcp_f32_e32 v150, v148
	v_rcp_f32_e32 v151, v149
	v_pk_fma_f32 v[140:141], v[136:137], v[138:139], 1.0 op_sel_hi:[1,1,0] neg_lo:[1,0,0] neg_hi:[1,0,0]
	v_pk_fma_f32 v[152:153], v[148:149], v[150:151], 1.0 op_sel_hi:[1,1,0] neg_lo:[1,0,0] neg_hi:[1,0,0]
	v_pk_fma_f32 v[138:139], v[140:141], v[138:139], v[138:139]
	v_pk_fma_f32 v[150:151], v[152:153], v[150:151], v[150:151]
	v_div_scale_f32 v142, s[28:29], v106, v134, v106
	v_div_scale_f32 v143, s[30:31], v107, v135, v107
	v_div_scale_f32 v154, s[2:3], v74, v146, v74
	v_div_scale_f32 v155, s[100:101], v75, v147, v75
	v_pk_mul_f32 v[144:145], v[142:143], v[138:139]
	v_pk_mul_f32 v[156:157], v[154:155], v[150:151]
	v_pk_fma_f32 v[140:141], v[136:137], v[144:145], v[142:143] neg_lo:[1,0,0] neg_hi:[1,0,0]
	v_pk_fma_f32 v[152:153], v[148:149], v[156:157], v[154:155] neg_lo:[1,0,0] neg_hi:[1,0,0]
	v_pk_fma_f32 v[144:145], v[140:141], v[138:139], v[144:145]
	v_pk_fma_f32 v[156:157], v[152:153], v[150:151], v[156:157]
	v_pk_fma_f32 v[136:137], v[136:137], v[144:145], v[142:143] neg_lo:[1,0,0] neg_hi:[1,0,0]
	v_pk_fma_f32 v[148:149], v[148:149], v[156:157], v[154:155] neg_lo:[1,0,0] neg_hi:[1,0,0]
	s_mov_b64 vcc, s[28:29]
	v_div_fmas_f32 v136, v136, v138, v144
	s_mov_b64 vcc, s[30:31]
	v_div_fmas_f32 v137, v137, v139, v145
	s_mov_b64 vcc, s[2:3]
	v_div_fmas_f32 v148, v148, v150, v156
	s_mov_b64 vcc, s[100:101]
	v_div_fmas_f32 v149, v149, v151, v157
	v_div_fixup_f32 v134, v136, v134, v106
	v_div_fixup_f32 v135, v137, v135, v107
	v_div_fixup_f32 v146, v148, v146, v74
	v_div_fixup_f32 v147, v149, v147, v75
	v_cvt_pk_bf16_f32 v136, v134, v135
	v_cvt_pk_bf16_f32 v148, v146, v147
	ds_write_b16 v159, v136 offset:4480
	ds_write_b16_d16_hi v159, v136 offset:4752
	ds_write_b16 v159, v148 offset:4544
	ds_write_b16_d16_hi v159, v148 offset:4816
	v_mul_f32_e32 v134, 0xbfb8aa3b, v124
	v_mul_f32_e32 v135, 0xbfb8aa3b, v125
	v_mul_f32_e32 v146, 0xbfb8aa3b, v92
	v_mul_f32_e32 v147, 0xbfb8aa3b, v93
	v_exp_f32_e32 v134, v134
	v_exp_f32_e32 v135, v135
	v_exp_f32_e32 v146, v146
	v_exp_f32_e32 v147, v147
	v_pk_add_f32 v[134:135], v[134:135], 1.0 op_sel_hi:[1,0]
	v_pk_add_f32 v[146:147], v[146:147], 1.0 op_sel_hi:[1,0]
	v_div_scale_f32 v136, vcc, v134, v134, v124
	v_div_scale_f32 v137, vcc, v135, v135, v125
	v_div_scale_f32 v148, vcc, v146, v146, v92
	v_div_scale_f32 v149, vcc, v147, v147, v93
	v_rcp_f32_e32 v138, v136
	v_rcp_f32_e32 v139, v137
	v_rcp_f32_e32 v150, v148
	v_rcp_f32_e32 v151, v149
	v_pk_fma_f32 v[140:141], v[136:137], v[138:139], 1.0 op_sel_hi:[1,1,0] neg_lo:[1,0,0] neg_hi:[1,0,0]
	v_pk_fma_f32 v[152:153], v[148:149], v[150:151], 1.0 op_sel_hi:[1,1,0] neg_lo:[1,0,0] neg_hi:[1,0,0]
	v_pk_fma_f32 v[138:139], v[140:141], v[138:139], v[138:139]
	v_pk_fma_f32 v[150:151], v[152:153], v[150:151], v[150:151]
	v_div_scale_f32 v142, s[28:29], v124, v134, v124
	v_div_scale_f32 v143, s[30:31], v125, v135, v125
	v_div_scale_f32 v154, s[2:3], v92, v146, v92
	v_div_scale_f32 v155, s[100:101], v93, v147, v93
	v_pk_mul_f32 v[144:145], v[142:143], v[138:139]
	v_pk_mul_f32 v[156:157], v[154:155], v[150:151]
	v_pk_fma_f32 v[140:141], v[136:137], v[144:145], v[142:143] neg_lo:[1,0,0] neg_hi:[1,0,0]
	v_pk_fma_f32 v[152:153], v[148:149], v[156:157], v[154:155] neg_lo:[1,0,0] neg_hi:[1,0,0]
	v_pk_fma_f32 v[144:145], v[140:141], v[138:139], v[144:145]
	v_pk_fma_f32 v[156:157], v[152:153], v[150:151], v[156:157]
	v_pk_fma_f32 v[136:137], v[136:137], v[144:145], v[142:143] neg_lo:[1,0,0] neg_hi:[1,0,0]
	v_pk_fma_f32 v[148:149], v[148:149], v[156:157], v[154:155] neg_lo:[1,0,0] neg_hi:[1,0,0]
	s_mov_b64 vcc, s[28:29]
	v_div_fmas_f32 v136, v136, v138, v144
	s_mov_b64 vcc, s[30:31]
	v_div_fmas_f32 v137, v137, v139, v145
	s_mov_b64 vcc, s[2:3]
	v_div_fmas_f32 v148, v148, v150, v156
	s_mov_b64 vcc, s[100:101]
	v_div_fmas_f32 v149, v149, v151, v157
	v_div_fixup_f32 v134, v136, v134, v124
	v_div_fixup_f32 v135, v137, v135, v125
	v_div_fixup_f32 v146, v148, v146, v92
	v_div_fixup_f32 v147, v149, v147, v93
	v_cvt_pk_bf16_f32 v136, v134, v135
	v_cvt_pk_bf16_f32 v148, v146, v147
	ds_write_b16 v159, v136 offset:4896
	ds_write_b16_d16_hi v159, v136 offset:5168
	ds_write_b16 v159, v148 offset:4960
	ds_write_b16_d16_hi v159, v148 offset:5232
	v_mul_f32_e32 v134, 0xbfb8aa3b, v108
	v_mul_f32_e32 v135, 0xbfb8aa3b, v109
	v_mul_f32_e32 v146, 0xbfb8aa3b, v76
	v_mul_f32_e32 v147, 0xbfb8aa3b, v77
	v_exp_f32_e32 v134, v134
	v_exp_f32_e32 v135, v135
	v_exp_f32_e32 v146, v146
	v_exp_f32_e32 v147, v147
	v_pk_add_f32 v[134:135], v[134:135], 1.0 op_sel_hi:[1,0]
	v_pk_add_f32 v[146:147], v[146:147], 1.0 op_sel_hi:[1,0]
	v_div_scale_f32 v136, vcc, v134, v134, v108
	v_div_scale_f32 v137, vcc, v135, v135, v109
	v_div_scale_f32 v148, vcc, v146, v146, v76
	v_div_scale_f32 v149, vcc, v147, v147, v77
	v_rcp_f32_e32 v138, v136
	v_rcp_f32_e32 v139, v137
	v_rcp_f32_e32 v150, v148
	v_rcp_f32_e32 v151, v149
	v_pk_fma_f32 v[140:141], v[136:137], v[138:139], 1.0 op_sel_hi:[1,1,0] neg_lo:[1,0,0] neg_hi:[1,0,0]
	v_pk_fma_f32 v[152:153], v[148:149], v[150:151], 1.0 op_sel_hi:[1,1,0] neg_lo:[1,0,0] neg_hi:[1,0,0]
	v_pk_fma_f32 v[138:139], v[140:141], v[138:139], v[138:139]
	v_pk_fma_f32 v[150:151], v[152:153], v[150:151], v[150:151]
	v_div_scale_f32 v142, s[28:29], v108, v134, v108
	v_div_scale_f32 v143, s[30:31], v109, v135, v109
	v_div_scale_f32 v154, s[2:3], v76, v146, v76
	v_div_scale_f32 v155, s[100:101], v77, v147, v77
	v_pk_mul_f32 v[144:145], v[142:143], v[138:139]
	v_pk_mul_f32 v[156:157], v[154:155], v[150:151]
	v_pk_fma_f32 v[140:141], v[136:137], v[144:145], v[142:143] neg_lo:[1,0,0] neg_hi:[1,0,0]
	v_pk_fma_f32 v[152:153], v[148:149], v[156:157], v[154:155] neg_lo:[1,0,0] neg_hi:[1,0,0]
	v_pk_fma_f32 v[144:145], v[140:141], v[138:139], v[144:145]
	v_pk_fma_f32 v[156:157], v[152:153], v[150:151], v[156:157]
	v_pk_fma_f32 v[136:137], v[136:137], v[144:145], v[142:143] neg_lo:[1,0,0] neg_hi:[1,0,0]
	v_pk_fma_f32 v[148:149], v[148:149], v[156:157], v[154:155] neg_lo:[1,0,0] neg_hi:[1,0,0]
	s_mov_b64 vcc, s[28:29]
	v_div_fmas_f32 v136, v136, v138, v144
	s_mov_b64 vcc, s[30:31]
	v_div_fmas_f32 v137, v137, v139, v145
	s_mov_b64 vcc, s[2:3]
	v_div_fmas_f32 v148, v148, v150, v156
	s_mov_b64 vcc, s[100:101]
	v_div_fmas_f32 v149, v149, v151, v157
	v_div_fixup_f32 v134, v136, v134, v108
	v_div_fixup_f32 v135, v137, v135, v109
	v_div_fixup_f32 v146, v148, v146, v76
	v_div_fixup_f32 v147, v149, v147, v77
	v_cvt_pk_bf16_f32 v136, v134, v135
	v_cvt_pk_bf16_f32 v148, v146, v147
	ds_write_b16 v159, v136 offset:5024
	ds_write_b16_d16_hi v159, v136 offset:5296
	ds_write_b16 v159, v148 offset:5088
	ds_write_b16_d16_hi v159, v148 offset:5360
	v_mul_f32_e32 v134, 0xbfb8aa3b, v126
	v_mul_f32_e32 v135, 0xbfb8aa3b, v127
	v_mul_f32_e32 v146, 0xbfb8aa3b, v94
	v_mul_f32_e32 v147, 0xbfb8aa3b, v95
	v_exp_f32_e32 v134, v134
	v_exp_f32_e32 v135, v135
	v_exp_f32_e32 v146, v146
	v_exp_f32_e32 v147, v147
	v_pk_add_f32 v[134:135], v[134:135], 1.0 op_sel_hi:[1,0]
	v_pk_add_f32 v[146:147], v[146:147], 1.0 op_sel_hi:[1,0]
	v_div_scale_f32 v136, vcc, v134, v134, v126
	v_div_scale_f32 v137, vcc, v135, v135, v127
	v_div_scale_f32 v148, vcc, v146, v146, v94
	v_div_scale_f32 v149, vcc, v147, v147, v95
	v_rcp_f32_e32 v138, v136
	v_rcp_f32_e32 v139, v137
	v_rcp_f32_e32 v150, v148
	v_rcp_f32_e32 v151, v149
	v_pk_fma_f32 v[140:141], v[136:137], v[138:139], 1.0 op_sel_hi:[1,1,0] neg_lo:[1,0,0] neg_hi:[1,0,0]
	v_pk_fma_f32 v[152:153], v[148:149], v[150:151], 1.0 op_sel_hi:[1,1,0] neg_lo:[1,0,0] neg_hi:[1,0,0]
	v_pk_fma_f32 v[138:139], v[140:141], v[138:139], v[138:139]
	v_pk_fma_f32 v[150:151], v[152:153], v[150:151], v[150:151]
	v_div_scale_f32 v142, s[28:29], v126, v134, v126
	v_div_scale_f32 v143, s[30:31], v127, v135, v127
	v_div_scale_f32 v154, s[2:3], v94, v146, v94
	v_div_scale_f32 v155, s[100:101], v95, v147, v95
	v_pk_mul_f32 v[144:145], v[142:143], v[138:139]
	v_pk_mul_f32 v[156:157], v[154:155], v[150:151]
	v_pk_fma_f32 v[140:141], v[136:137], v[144:145], v[142:143] neg_lo:[1,0,0] neg_hi:[1,0,0]
	v_pk_fma_f32 v[152:153], v[148:149], v[156:157], v[154:155] neg_lo:[1,0,0] neg_hi:[1,0,0]
	v_pk_fma_f32 v[144:145], v[140:141], v[138:139], v[144:145]
	v_pk_fma_f32 v[156:157], v[152:153], v[150:151], v[156:157]
	v_pk_fma_f32 v[136:137], v[136:137], v[144:145], v[142:143] neg_lo:[1,0,0] neg_hi:[1,0,0]
	v_pk_fma_f32 v[148:149], v[148:149], v[156:157], v[154:155] neg_lo:[1,0,0] neg_hi:[1,0,0]
	s_mov_b64 vcc, s[28:29]
	v_div_fmas_f32 v136, v136, v138, v144
	s_mov_b64 vcc, s[30:31]
	v_div_fmas_f32 v137, v137, v139, v145
	s_mov_b64 vcc, s[2:3]
	v_div_fmas_f32 v148, v148, v150, v156
	s_mov_b64 vcc, s[100:101]
	v_div_fmas_f32 v149, v149, v151, v157
	v_div_fixup_f32 v134, v136, v134, v126
	v_div_fixup_f32 v135, v137, v135, v127
	v_div_fixup_f32 v146, v148, v146, v94
	v_div_fixup_f32 v147, v149, v147, v95
	v_cvt_pk_bf16_f32 v136, v134, v135
	v_cvt_pk_bf16_f32 v148, v146, v147
	ds_write_b16 v159, v136 offset:6528
	ds_write_b16_d16_hi v159, v136 offset:6800
	ds_write_b16 v159, v148 offset:6592
	ds_write_b16_d16_hi v159, v148 offset:6864
	v_mul_f32_e32 v134, 0xbfb8aa3b, v110
	v_mul_f32_e32 v135, 0xbfb8aa3b, v111
	v_mul_f32_e32 v146, 0xbfb8aa3b, v78
	v_mul_f32_e32 v147, 0xbfb8aa3b, v79
	v_exp_f32_e32 v134, v134
	v_exp_f32_e32 v135, v135
	v_exp_f32_e32 v146, v146
	v_exp_f32_e32 v147, v147
	v_pk_add_f32 v[134:135], v[134:135], 1.0 op_sel_hi:[1,0]
	v_pk_add_f32 v[146:147], v[146:147], 1.0 op_sel_hi:[1,0]
	v_div_scale_f32 v136, vcc, v134, v134, v110
	v_div_scale_f32 v137, vcc, v135, v135, v111
	v_div_scale_f32 v148, vcc, v146, v146, v78
	v_div_scale_f32 v149, vcc, v147, v147, v79
	v_rcp_f32_e32 v138, v136
	v_rcp_f32_e32 v139, v137
	v_rcp_f32_e32 v150, v148
	v_rcp_f32_e32 v151, v149
	v_pk_fma_f32 v[140:141], v[136:137], v[138:139], 1.0 op_sel_hi:[1,1,0] neg_lo:[1,0,0] neg_hi:[1,0,0]
	v_pk_fma_f32 v[152:153], v[148:149], v[150:151], 1.0 op_sel_hi:[1,1,0] neg_lo:[1,0,0] neg_hi:[1,0,0]
	v_pk_fma_f32 v[138:139], v[140:141], v[138:139], v[138:139]
	v_pk_fma_f32 v[150:151], v[152:153], v[150:151], v[150:151]
	v_div_scale_f32 v142, s[28:29], v110, v134, v110
	v_div_scale_f32 v143, s[30:31], v111, v135, v111
	v_div_scale_f32 v154, s[2:3], v78, v146, v78
	v_div_scale_f32 v155, s[100:101], v79, v147, v79
	v_pk_mul_f32 v[144:145], v[142:143], v[138:139]
	v_pk_mul_f32 v[156:157], v[154:155], v[150:151]
	v_pk_fma_f32 v[140:141], v[136:137], v[144:145], v[142:143] neg_lo:[1,0,0] neg_hi:[1,0,0]
	v_pk_fma_f32 v[152:153], v[148:149], v[156:157], v[154:155] neg_lo:[1,0,0] neg_hi:[1,0,0]
	v_pk_fma_f32 v[144:145], v[140:141], v[138:139], v[144:145]
	v_pk_fma_f32 v[156:157], v[152:153], v[150:151], v[156:157]
	v_pk_fma_f32 v[136:137], v[136:137], v[144:145], v[142:143] neg_lo:[1,0,0] neg_hi:[1,0,0]
	v_pk_fma_f32 v[148:149], v[148:149], v[156:157], v[154:155] neg_lo:[1,0,0] neg_hi:[1,0,0]
	s_mov_b64 vcc, s[28:29]
	v_div_fmas_f32 v136, v136, v138, v144
	s_mov_b64 vcc, s[30:31]
	v_div_fmas_f32 v137, v137, v139, v145
	s_mov_b64 vcc, s[2:3]
	v_div_fmas_f32 v148, v148, v150, v156
	s_mov_b64 vcc, s[100:101]
	v_div_fmas_f32 v149, v149, v151, v157
	v_div_fixup_f32 v134, v136, v134, v110
	v_div_fixup_f32 v135, v137, v135, v111
	v_div_fixup_f32 v146, v148, v146, v78
	v_div_fixup_f32 v147, v149, v147, v79
	v_cvt_pk_bf16_f32 v136, v134, v135
	v_cvt_pk_bf16_f32 v148, v146, v147
	ds_write_b16 v159, v136 offset:6656
	ds_write_b16_d16_hi v159, v136 offset:6928
	ds_write_b16 v159, v148 offset:6720
	ds_write_b16_d16_hi v159, v148 offset:6992
	v_mul_f32_e32 v134, 0xbfb8aa3b, v128
	v_mul_f32_e32 v135, 0xbfb8aa3b, v129
	v_mul_f32_e32 v146, 0xbfb8aa3b, v96
	v_mul_f32_e32 v147, 0xbfb8aa3b, v97
	v_exp_f32_e32 v134, v134
	v_exp_f32_e32 v135, v135
	v_exp_f32_e32 v146, v146
	v_exp_f32_e32 v147, v147
	v_pk_add_f32 v[134:135], v[134:135], 1.0 op_sel_hi:[1,0]
	v_pk_add_f32 v[146:147], v[146:147], 1.0 op_sel_hi:[1,0]
	v_div_scale_f32 v136, vcc, v134, v134, v128
	v_div_scale_f32 v137, vcc, v135, v135, v129
	v_div_scale_f32 v148, vcc, v146, v146, v96
	v_div_scale_f32 v149, vcc, v147, v147, v97
	v_rcp_f32_e32 v138, v136
	v_rcp_f32_e32 v139, v137
	v_rcp_f32_e32 v150, v148
	v_rcp_f32_e32 v151, v149
	v_pk_fma_f32 v[140:141], v[136:137], v[138:139], 1.0 op_sel_hi:[1,1,0] neg_lo:[1,0,0] neg_hi:[1,0,0]
	v_pk_fma_f32 v[152:153], v[148:149], v[150:151], 1.0 op_sel_hi:[1,1,0] neg_lo:[1,0,0] neg_hi:[1,0,0]
	v_pk_fma_f32 v[138:139], v[140:141], v[138:139], v[138:139]
	v_pk_fma_f32 v[150:151], v[152:153], v[150:151], v[150:151]
	v_div_scale_f32 v142, s[28:29], v128, v134, v128
	v_div_scale_f32 v143, s[30:31], v129, v135, v129
	v_div_scale_f32 v154, s[2:3], v96, v146, v96
	v_div_scale_f32 v155, s[100:101], v97, v147, v97
	v_pk_mul_f32 v[144:145], v[142:143], v[138:139]
	v_pk_mul_f32 v[156:157], v[154:155], v[150:151]
	v_pk_fma_f32 v[140:141], v[136:137], v[144:145], v[142:143] neg_lo:[1,0,0] neg_hi:[1,0,0]
	v_pk_fma_f32 v[152:153], v[148:149], v[156:157], v[154:155] neg_lo:[1,0,0] neg_hi:[1,0,0]
	v_pk_fma_f32 v[144:145], v[140:141], v[138:139], v[144:145]
	v_pk_fma_f32 v[156:157], v[152:153], v[150:151], v[156:157]
	v_pk_fma_f32 v[136:137], v[136:137], v[144:145], v[142:143] neg_lo:[1,0,0] neg_hi:[1,0,0]
	v_pk_fma_f32 v[148:149], v[148:149], v[156:157], v[154:155] neg_lo:[1,0,0] neg_hi:[1,0,0]
	s_mov_b64 vcc, s[28:29]
	v_div_fmas_f32 v136, v136, v138, v144
	s_mov_b64 vcc, s[30:31]
	v_div_fmas_f32 v137, v137, v139, v145
	s_mov_b64 vcc, s[2:3]
	v_div_fmas_f32 v148, v148, v150, v156
	s_mov_b64 vcc, s[100:101]
	v_div_fmas_f32 v149, v149, v151, v157
	v_div_fixup_f32 v134, v136, v134, v128
	v_div_fixup_f32 v135, v137, v135, v129
	v_div_fixup_f32 v146, v148, v146, v96
	v_div_fixup_f32 v147, v149, v147, v97
	v_cvt_pk_bf16_f32 v136, v134, v135
	v_cvt_pk_bf16_f32 v148, v146, v147
	ds_write_b16 v159, v136 offset:7072
	ds_write_b16_d16_hi v159, v136 offset:7344
	ds_write_b16 v159, v148 offset:7136
	ds_write_b16_d16_hi v159, v148 offset:7408
	v_mul_f32_e32 v134, 0xbfb8aa3b, v112
	v_mul_f32_e32 v135, 0xbfb8aa3b, v113
	v_mul_f32_e32 v146, 0xbfb8aa3b, v80
	v_mul_f32_e32 v147, 0xbfb8aa3b, v81
	v_exp_f32_e32 v134, v134
	v_exp_f32_e32 v135, v135
	v_exp_f32_e32 v146, v146
	v_exp_f32_e32 v147, v147
	v_pk_add_f32 v[134:135], v[134:135], 1.0 op_sel_hi:[1,0]
	v_pk_add_f32 v[146:147], v[146:147], 1.0 op_sel_hi:[1,0]
	v_div_scale_f32 v136, vcc, v134, v134, v112
	v_div_scale_f32 v137, vcc, v135, v135, v113
	v_div_scale_f32 v148, vcc, v146, v146, v80
	v_div_scale_f32 v149, vcc, v147, v147, v81
	v_rcp_f32_e32 v138, v136
	v_rcp_f32_e32 v139, v137
	v_rcp_f32_e32 v150, v148
	v_rcp_f32_e32 v151, v149
	v_pk_fma_f32 v[140:141], v[136:137], v[138:139], 1.0 op_sel_hi:[1,1,0] neg_lo:[1,0,0] neg_hi:[1,0,0]
	v_pk_fma_f32 v[152:153], v[148:149], v[150:151], 1.0 op_sel_hi:[1,1,0] neg_lo:[1,0,0] neg_hi:[1,0,0]
	v_pk_fma_f32 v[138:139], v[140:141], v[138:139], v[138:139]
	v_pk_fma_f32 v[150:151], v[152:153], v[150:151], v[150:151]
	v_div_scale_f32 v142, s[28:29], v112, v134, v112
	v_div_scale_f32 v143, s[30:31], v113, v135, v113
	v_div_scale_f32 v154, s[2:3], v80, v146, v80
	v_div_scale_f32 v155, s[100:101], v81, v147, v81
	v_pk_mul_f32 v[144:145], v[142:143], v[138:139]
	v_pk_mul_f32 v[156:157], v[154:155], v[150:151]
	v_pk_fma_f32 v[140:141], v[136:137], v[144:145], v[142:143] neg_lo:[1,0,0] neg_hi:[1,0,0]
	v_pk_fma_f32 v[152:153], v[148:149], v[156:157], v[154:155] neg_lo:[1,0,0] neg_hi:[1,0,0]
	v_pk_fma_f32 v[144:145], v[140:141], v[138:139], v[144:145]
	v_pk_fma_f32 v[156:157], v[152:153], v[150:151], v[156:157]
	v_pk_fma_f32 v[136:137], v[136:137], v[144:145], v[142:143] neg_lo:[1,0,0] neg_hi:[1,0,0]
	v_pk_fma_f32 v[148:149], v[148:149], v[156:157], v[154:155] neg_lo:[1,0,0] neg_hi:[1,0,0]
	s_mov_b64 vcc, s[28:29]
	v_div_fmas_f32 v136, v136, v138, v144
	s_mov_b64 vcc, s[30:31]
	v_div_fmas_f32 v137, v137, v139, v145
	s_mov_b64 vcc, s[2:3]
	v_div_fmas_f32 v148, v148, v150, v156
	s_mov_b64 vcc, s[100:101]
	v_div_fmas_f32 v149, v149, v151, v157
	v_div_fixup_f32 v134, v136, v134, v112
	v_div_fixup_f32 v135, v137, v135, v113
	v_div_fixup_f32 v146, v148, v146, v80
	v_div_fixup_f32 v147, v149, v147, v81
	v_cvt_pk_bf16_f32 v136, v134, v135
	v_cvt_pk_bf16_f32 v148, v146, v147
	ds_write_b16 v159, v136 offset:7200
	ds_write_b16_d16_hi v159, v136 offset:7472
	ds_write_b16 v159, v148 offset:7264
	ds_write_b16_d16_hi v159, v148 offset:7536
	s_mov_b64 s[100:101], 0x4000
	s_waitcnt lgkmcnt(0)
	ds_read_b128 v[164:167], v160 offset:0
	ds_read_b128 v[168:171], v160 offset:1088
	ds_read_b128 v[172:175], v160 offset:2176
	ds_read_b128 v[224:227], v160 offset:3264
	ds_read_b128 v[228:231], v160 offset:4352
	ds_read_b128 v[232:235], v160 offset:5440
	ds_read_b128 v[236:239], v160 offset:6528
	ds_read_b128 v[240:243], v160 offset:7616
	s_waitcnt lgkmcnt(7)
	global_store_dwordx4 v[162:163], v[164:167], off
	v_lshl_add_u64 v[162:163], v[162:163], 0, s[100:101]
	s_waitcnt lgkmcnt(6)
	global_store_dwordx4 v[162:163], v[168:171], off
	v_lshl_add_u64 v[162:163], v[162:163], 0, s[100:101]
	s_waitcnt lgkmcnt(5)
	global_store_dwordx4 v[162:163], v[172:175], off
	v_lshl_add_u64 v[162:163], v[162:163], 0, s[100:101]
	s_waitcnt lgkmcnt(4)
	global_store_dwordx4 v[162:163], v[224:227], off
	v_lshl_add_u64 v[162:163], v[162:163], 0, s[100:101]
	s_waitcnt lgkmcnt(3)
	global_store_dwordx4 v[162:163], v[228:231], off
	v_lshl_add_u64 v[162:163], v[162:163], 0, s[100:101]
	s_waitcnt lgkmcnt(2)
	global_store_dwordx4 v[162:163], v[232:235], off
	v_lshl_add_u64 v[162:163], v[162:163], 0, s[100:101]
	s_waitcnt lgkmcnt(1)
	global_store_dwordx4 v[162:163], v[236:239], off
	v_lshl_add_u64 v[162:163], v[162:163], 0, s[100:101]
	s_waitcnt lgkmcnt(0)
	global_store_dwordx4 v[162:163], v[240:243], off
	v_lshl_add_u64 v[162:163], v[162:163], 0, s[100:101]
	v_mul_f32_e32 v134, 0xbfb8aa3b, v50
	v_mul_f32_e32 v135, 0xbfb8aa3b, v51
	v_mul_f32_e32 v146, 0xbfb8aa3b, v16
	v_mul_f32_e32 v147, 0xbfb8aa3b, v17
	v_exp_f32_e32 v134, v134
	v_exp_f32_e32 v135, v135
	v_exp_f32_e32 v146, v146
	v_exp_f32_e32 v147, v147
	v_pk_add_f32 v[134:135], v[134:135], 1.0 op_sel_hi:[1,0]
	v_pk_add_f32 v[146:147], v[146:147], 1.0 op_sel_hi:[1,0]
	v_div_scale_f32 v136, vcc, v134, v134, v50
	v_div_scale_f32 v137, vcc, v135, v135, v51
	v_div_scale_f32 v148, vcc, v146, v146, v16
	v_div_scale_f32 v149, vcc, v147, v147, v17
	v_rcp_f32_e32 v138, v136
	v_rcp_f32_e32 v139, v137
	v_rcp_f32_e32 v150, v148
	v_rcp_f32_e32 v151, v149
	v_pk_fma_f32 v[140:141], v[136:137], v[138:139], 1.0 op_sel_hi:[1,1,0] neg_lo:[1,0,0] neg_hi:[1,0,0]
	v_pk_fma_f32 v[152:153], v[148:149], v[150:151], 1.0 op_sel_hi:[1,1,0] neg_lo:[1,0,0] neg_hi:[1,0,0]
	v_pk_fma_f32 v[138:139], v[140:141], v[138:139], v[138:139]
	v_pk_fma_f32 v[150:151], v[152:153], v[150:151], v[150:151]
	v_div_scale_f32 v142, s[28:29], v50, v134, v50
	v_div_scale_f32 v143, s[30:31], v51, v135, v51
	v_div_scale_f32 v154, s[2:3], v16, v146, v16
	v_div_scale_f32 v155, s[100:101], v17, v147, v17
	v_pk_mul_f32 v[144:145], v[142:143], v[138:139]
	v_pk_mul_f32 v[156:157], v[154:155], v[150:151]
	v_pk_fma_f32 v[140:141], v[136:137], v[144:145], v[142:143] neg_lo:[1,0,0] neg_hi:[1,0,0]
	v_pk_fma_f32 v[152:153], v[148:149], v[156:157], v[154:155] neg_lo:[1,0,0] neg_hi:[1,0,0]
	v_pk_fma_f32 v[144:145], v[140:141], v[138:139], v[144:145]
	v_pk_fma_f32 v[156:157], v[152:153], v[150:151], v[156:157]
	v_pk_fma_f32 v[136:137], v[136:137], v[144:145], v[142:143] neg_lo:[1,0,0] neg_hi:[1,0,0]
	v_pk_fma_f32 v[148:149], v[148:149], v[156:157], v[154:155] neg_lo:[1,0,0] neg_hi:[1,0,0]
	s_mov_b64 vcc, s[28:29]
	v_div_fmas_f32 v136, v136, v138, v144
	s_mov_b64 vcc, s[30:31]
	v_div_fmas_f32 v137, v137, v139, v145
	s_mov_b64 vcc, s[2:3]
	v_div_fmas_f32 v148, v148, v150, v156
	s_mov_b64 vcc, s[100:101]
	v_div_fmas_f32 v149, v149, v151, v157
	v_div_fixup_f32 v134, v136, v134, v50
	v_div_fixup_f32 v135, v137, v135, v51
	v_div_fixup_f32 v146, v148, v146, v16
	v_div_fixup_f32 v147, v149, v147, v17
	v_cvt_pk_bf16_f32 v136, v134, v135
	v_cvt_pk_bf16_f32 v148, v146, v147
	ds_write_b16 v159, v136 offset:0
	ds_write_b16_d16_hi v159, v136 offset:272
	ds_write_b16 v159, v148 offset:64
	ds_write_b16_d16_hi v159, v148 offset:336
	v_mul_f32_e32 v134, 0xbfb8aa3b, v34
	v_mul_f32_e32 v135, 0xbfb8aa3b, v35
	v_mul_f32_e32 v146, 0xbfb8aa3b, v0
	v_mul_f32_e32 v147, 0xbfb8aa3b, v1
	v_exp_f32_e32 v134, v134
	v_exp_f32_e32 v135, v135
	v_exp_f32_e32 v146, v146
	v_exp_f32_e32 v147, v147
	v_pk_add_f32 v[134:135], v[134:135], 1.0 op_sel_hi:[1,0]
	v_pk_add_f32 v[146:147], v[146:147], 1.0 op_sel_hi:[1,0]
	v_div_scale_f32 v136, vcc, v134, v134, v34
	v_div_scale_f32 v137, vcc, v135, v135, v35
	v_div_scale_f32 v148, vcc, v146, v146, v0
	v_div_scale_f32 v149, vcc, v147, v147, v1
	v_rcp_f32_e32 v138, v136
	v_rcp_f32_e32 v139, v137
	v_rcp_f32_e32 v150, v148
	v_rcp_f32_e32 v151, v149
	v_pk_fma_f32 v[140:141], v[136:137], v[138:139], 1.0 op_sel_hi:[1,1,0] neg_lo:[1,0,0] neg_hi:[1,0,0]
	v_pk_fma_f32 v[152:153], v[148:149], v[150:151], 1.0 op_sel_hi:[1,1,0] neg_lo:[1,0,0] neg_hi:[1,0,0]
	v_pk_fma_f32 v[138:139], v[140:141], v[138:139], v[138:139]
	v_pk_fma_f32 v[150:151], v[152:153], v[150:151], v[150:151]
	v_div_scale_f32 v142, s[28:29], v34, v134, v34
	v_div_scale_f32 v143, s[30:31], v35, v135, v35
	v_div_scale_f32 v154, s[2:3], v0, v146, v0
	v_div_scale_f32 v155, s[100:101], v1, v147, v1
	v_pk_mul_f32 v[144:145], v[142:143], v[138:139]
	v_pk_mul_f32 v[156:157], v[154:155], v[150:151]
	v_pk_fma_f32 v[140:141], v[136:137], v[144:145], v[142:143] neg_lo:[1,0,0] neg_hi:[1,0,0]
	v_pk_fma_f32 v[152:153], v[148:149], v[156:157], v[154:155] neg_lo:[1,0,0] neg_hi:[1,0,0]
	v_pk_fma_f32 v[144:145], v[140:141], v[138:139], v[144:145]
	v_pk_fma_f32 v[156:157], v[152:153], v[150:151], v[156:157]
	v_pk_fma_f32 v[136:137], v[136:137], v[144:145], v[142:143] neg_lo:[1,0,0] neg_hi:[1,0,0]
	v_pk_fma_f32 v[148:149], v[148:149], v[156:157], v[154:155] neg_lo:[1,0,0] neg_hi:[1,0,0]
	s_mov_b64 vcc, s[28:29]
	v_div_fmas_f32 v136, v136, v138, v144
	s_mov_b64 vcc, s[30:31]
	v_div_fmas_f32 v137, v137, v139, v145
	s_mov_b64 vcc, s[2:3]
	v_div_fmas_f32 v148, v148, v150, v156
	s_mov_b64 vcc, s[100:101]
	v_div_fmas_f32 v149, v149, v151, v157
	v_div_fixup_f32 v134, v136, v134, v34
	v_div_fixup_f32 v135, v137, v135, v35
	v_div_fixup_f32 v146, v148, v146, v0
	v_div_fixup_f32 v147, v149, v147, v1
	v_cvt_pk_bf16_f32 v136, v134, v135
	v_cvt_pk_bf16_f32 v148, v146, v147
	ds_write_b16 v159, v136 offset:128
	ds_write_b16_d16_hi v159, v136 offset:400
	ds_write_b16 v159, v148 offset:192
	ds_write_b16_d16_hi v159, v148 offset:464
	v_mul_f32_e32 v134, 0xbfb8aa3b, v52
	v_mul_f32_e32 v135, 0xbfb8aa3b, v53
	v_mul_f32_e32 v146, 0xbfb8aa3b, v18
	v_mul_f32_e32 v147, 0xbfb8aa3b, v19
	v_exp_f32_e32 v134, v134
	v_exp_f32_e32 v135, v135
	v_exp_f32_e32 v146, v146
	v_exp_f32_e32 v147, v147
	v_pk_add_f32 v[134:135], v[134:135], 1.0 op_sel_hi:[1,0]
	v_pk_add_f32 v[146:147], v[146:147], 1.0 op_sel_hi:[1,0]
	v_div_scale_f32 v136, vcc, v134, v134, v52
	v_div_scale_f32 v137, vcc, v135, v135, v53
	v_div_scale_f32 v148, vcc, v146, v146, v18
	v_div_scale_f32 v149, vcc, v147, v147, v19
	v_rcp_f32_e32 v138, v136
	v_rcp_f32_e32 v139, v137
	v_rcp_f32_e32 v150, v148
	v_rcp_f32_e32 v151, v149
	v_pk_fma_f32 v[140:141], v[136:137], v[138:139], 1.0 op_sel_hi:[1,1,0] neg_lo:[1,0,0] neg_hi:[1,0,0]
	v_pk_fma_f32 v[152:153], v[148:149], v[150:151], 1.0 op_sel_hi:[1,1,0] neg_lo:[1,0,0] neg_hi:[1,0,0]
	v_pk_fma_f32 v[138:139], v[140:141], v[138:139], v[138:139]
	v_pk_fma_f32 v[150:151], v[152:153], v[150:151], v[150:151]
	v_div_scale_f32 v142, s[28:29], v52, v134, v52
	v_div_scale_f32 v143, s[30:31], v53, v135, v53
	v_div_scale_f32 v154, s[2:3], v18, v146, v18
	v_div_scale_f32 v155, s[100:101], v19, v147, v19
	v_pk_mul_f32 v[144:145], v[142:143], v[138:139]
	v_pk_mul_f32 v[156:157], v[154:155], v[150:151]
	v_pk_fma_f32 v[140:141], v[136:137], v[144:145], v[142:143] neg_lo:[1,0,0] neg_hi:[1,0,0]
	v_pk_fma_f32 v[152:153], v[148:149], v[156:157], v[154:155] neg_lo:[1,0,0] neg_hi:[1,0,0]
	v_pk_fma_f32 v[144:145], v[140:141], v[138:139], v[144:145]
	v_pk_fma_f32 v[156:157], v[152:153], v[150:151], v[156:157]
	v_pk_fma_f32 v[136:137], v[136:137], v[144:145], v[142:143] neg_lo:[1,0,0] neg_hi:[1,0,0]
	v_pk_fma_f32 v[148:149], v[148:149], v[156:157], v[154:155] neg_lo:[1,0,0] neg_hi:[1,0,0]
	s_mov_b64 vcc, s[28:29]
	v_div_fmas_f32 v136, v136, v138, v144
	s_mov_b64 vcc, s[30:31]
	v_div_fmas_f32 v137, v137, v139, v145
	s_mov_b64 vcc, s[2:3]
	v_div_fmas_f32 v148, v148, v150, v156
	s_mov_b64 vcc, s[100:101]
	v_div_fmas_f32 v149, v149, v151, v157
	v_div_fixup_f32 v134, v136, v134, v52
	v_div_fixup_f32 v135, v137, v135, v53
	v_div_fixup_f32 v146, v148, v146, v18
	v_div_fixup_f32 v147, v149, v147, v19
	v_cvt_pk_bf16_f32 v136, v134, v135
	v_cvt_pk_bf16_f32 v148, v146, v147
	ds_write_b16 v159, v136 offset:544
	ds_write_b16_d16_hi v159, v136 offset:816
	ds_write_b16 v159, v148 offset:608
	ds_write_b16_d16_hi v159, v148 offset:880
	v_mul_f32_e32 v134, 0xbfb8aa3b, v36
	v_mul_f32_e32 v135, 0xbfb8aa3b, v37
	v_mul_f32_e32 v146, 0xbfb8aa3b, v2
	v_mul_f32_e32 v147, 0xbfb8aa3b, v3
	v_exp_f32_e32 v134, v134
	v_exp_f32_e32 v135, v135
	v_exp_f32_e32 v146, v146
	v_exp_f32_e32 v147, v147
	v_pk_add_f32 v[134:135], v[134:135], 1.0 op_sel_hi:[1,0]
	v_pk_add_f32 v[146:147], v[146:147], 1.0 op_sel_hi:[1,0]
	v_div_scale_f32 v136, vcc, v134, v134, v36
	v_div_scale_f32 v137, vcc, v135, v135, v37
	v_div_scale_f32 v148, vcc, v146, v146, v2
	v_div_scale_f32 v149, vcc, v147, v147, v3
	v_rcp_f32_e32 v138, v136
	v_rcp_f32_e32 v139, v137
	v_rcp_f32_e32 v150, v148
	v_rcp_f32_e32 v151, v149
	v_pk_fma_f32 v[140:141], v[136:137], v[138:139], 1.0 op_sel_hi:[1,1,0] neg_lo:[1,0,0] neg_hi:[1,0,0]
	v_pk_fma_f32 v[152:153], v[148:149], v[150:151], 1.0 op_sel_hi:[1,1,0] neg_lo:[1,0,0] neg_hi:[1,0,0]
	v_pk_fma_f32 v[138:139], v[140:141], v[138:139], v[138:139]
	v_pk_fma_f32 v[150:151], v[152:153], v[150:151], v[150:151]
	v_div_scale_f32 v142, s[28:29], v36, v134, v36
	v_div_scale_f32 v143, s[30:31], v37, v135, v37
	v_div_scale_f32 v154, s[2:3], v2, v146, v2
	v_div_scale_f32 v155, s[100:101], v3, v147, v3
	v_pk_mul_f32 v[144:145], v[142:143], v[138:139]
	v_pk_mul_f32 v[156:157], v[154:155], v[150:151]
	v_pk_fma_f32 v[140:141], v[136:137], v[144:145], v[142:143] neg_lo:[1,0,0] neg_hi:[1,0,0]
	v_pk_fma_f32 v[152:153], v[148:149], v[156:157], v[154:155] neg_lo:[1,0,0] neg_hi:[1,0,0]
	v_pk_fma_f32 v[144:145], v[140:141], v[138:139], v[144:145]
	v_pk_fma_f32 v[156:157], v[152:153], v[150:151], v[156:157]
	v_pk_fma_f32 v[136:137], v[136:137], v[144:145], v[142:143] neg_lo:[1,0,0] neg_hi:[1,0,0]
	v_pk_fma_f32 v[148:149], v[148:149], v[156:157], v[154:155] neg_lo:[1,0,0] neg_hi:[1,0,0]
	s_mov_b64 vcc, s[28:29]
	v_div_fmas_f32 v136, v136, v138, v144
	s_mov_b64 vcc, s[30:31]
	v_div_fmas_f32 v137, v137, v139, v145
	s_mov_b64 vcc, s[2:3]
	v_div_fmas_f32 v148, v148, v150, v156
	s_mov_b64 vcc, s[100:101]
	v_div_fmas_f32 v149, v149, v151, v157
	v_div_fixup_f32 v134, v136, v134, v36
	v_div_fixup_f32 v135, v137, v135, v37
	v_div_fixup_f32 v146, v148, v146, v2
	v_div_fixup_f32 v147, v149, v147, v3
	v_cvt_pk_bf16_f32 v136, v134, v135
	v_cvt_pk_bf16_f32 v148, v146, v147
	ds_write_b16 v159, v136 offset:672
	ds_write_b16_d16_hi v159, v136 offset:944
	ds_write_b16 v159, v148 offset:736
	ds_write_b16_d16_hi v159, v148 offset:1008
	v_mul_f32_e32 v134, 0xbfb8aa3b, v54
	v_mul_f32_e32 v135, 0xbfb8aa3b, v55
	v_mul_f32_e32 v146, 0xbfb8aa3b, v20
	v_mul_f32_e32 v147, 0xbfb8aa3b, v21
	v_exp_f32_e32 v134, v134
	v_exp_f32_e32 v135, v135
	v_exp_f32_e32 v146, v146
	v_exp_f32_e32 v147, v147
	v_pk_add_f32 v[134:135], v[134:135], 1.0 op_sel_hi:[1,0]
	v_pk_add_f32 v[146:147], v[146:147], 1.0 op_sel_hi:[1,0]
	v_div_scale_f32 v136, vcc, v134, v134, v54
	v_div_scale_f32 v137, vcc, v135, v135, v55
	v_div_scale_f32 v148, vcc, v146, v146, v20
	v_div_scale_f32 v149, vcc, v147, v147, v21
	v_rcp_f32_e32 v138, v136
	v_rcp_f32_e32 v139, v137
	v_rcp_f32_e32 v150, v148
	v_rcp_f32_e32 v151, v149
	v_pk_fma_f32 v[140:141], v[136:137], v[138:139], 1.0 op_sel_hi:[1,1,0] neg_lo:[1,0,0] neg_hi:[1,0,0]
	v_pk_fma_f32 v[152:153], v[148:149], v[150:151], 1.0 op_sel_hi:[1,1,0] neg_lo:[1,0,0] neg_hi:[1,0,0]
	v_pk_fma_f32 v[138:139], v[140:141], v[138:139], v[138:139]
	v_pk_fma_f32 v[150:151], v[152:153], v[150:151], v[150:151]
	v_div_scale_f32 v142, s[28:29], v54, v134, v54
	v_div_scale_f32 v143, s[30:31], v55, v135, v55
	v_div_scale_f32 v154, s[2:3], v20, v146, v20
	v_div_scale_f32 v155, s[100:101], v21, v147, v21
	v_pk_mul_f32 v[144:145], v[142:143], v[138:139]
	v_pk_mul_f32 v[156:157], v[154:155], v[150:151]
	v_pk_fma_f32 v[140:141], v[136:137], v[144:145], v[142:143] neg_lo:[1,0,0] neg_hi:[1,0,0]
	v_pk_fma_f32 v[152:153], v[148:149], v[156:157], v[154:155] neg_lo:[1,0,0] neg_hi:[1,0,0]
	v_pk_fma_f32 v[144:145], v[140:141], v[138:139], v[144:145]
	v_pk_fma_f32 v[156:157], v[152:153], v[150:151], v[156:157]
	v_pk_fma_f32 v[136:137], v[136:137], v[144:145], v[142:143] neg_lo:[1,0,0] neg_hi:[1,0,0]
	v_pk_fma_f32 v[148:149], v[148:149], v[156:157], v[154:155] neg_lo:[1,0,0] neg_hi:[1,0,0]
	s_mov_b64 vcc, s[28:29]
	v_div_fmas_f32 v136, v136, v138, v144
	s_mov_b64 vcc, s[30:31]
	v_div_fmas_f32 v137, v137, v139, v145
	s_mov_b64 vcc, s[2:3]
	v_div_fmas_f32 v148, v148, v150, v156
	s_mov_b64 vcc, s[100:101]
	v_div_fmas_f32 v149, v149, v151, v157
	v_div_fixup_f32 v134, v136, v134, v54
	v_div_fixup_f32 v135, v137, v135, v55
	v_div_fixup_f32 v146, v148, v146, v20
	v_div_fixup_f32 v147, v149, v147, v21
	v_cvt_pk_bf16_f32 v136, v134, v135
	v_cvt_pk_bf16_f32 v148, v146, v147
	ds_write_b16 v159, v136 offset:2176
	ds_write_b16_d16_hi v159, v136 offset:2448
	ds_write_b16 v159, v148 offset:2240
	ds_write_b16_d16_hi v159, v148 offset:2512
	v_mul_f32_e32 v134, 0xbfb8aa3b, v38
	v_mul_f32_e32 v135, 0xbfb8aa3b, v39
	v_mul_f32_e32 v146, 0xbfb8aa3b, v4
	v_mul_f32_e32 v147, 0xbfb8aa3b, v5
	v_exp_f32_e32 v134, v134
	v_exp_f32_e32 v135, v135
	v_exp_f32_e32 v146, v146
	v_exp_f32_e32 v147, v147
	v_pk_add_f32 v[134:135], v[134:135], 1.0 op_sel_hi:[1,0]
	v_pk_add_f32 v[146:147], v[146:147], 1.0 op_sel_hi:[1,0]
	v_div_scale_f32 v136, vcc, v134, v134, v38
	v_div_scale_f32 v137, vcc, v135, v135, v39
	v_div_scale_f32 v148, vcc, v146, v146, v4
	v_div_scale_f32 v149, vcc, v147, v147, v5
	v_rcp_f32_e32 v138, v136
	v_rcp_f32_e32 v139, v137
	v_rcp_f32_e32 v150, v148
	v_rcp_f32_e32 v151, v149
	v_pk_fma_f32 v[140:141], v[136:137], v[138:139], 1.0 op_sel_hi:[1,1,0] neg_lo:[1,0,0] neg_hi:[1,0,0]
	v_pk_fma_f32 v[152:153], v[148:149], v[150:151], 1.0 op_sel_hi:[1,1,0] neg_lo:[1,0,0] neg_hi:[1,0,0]
	v_pk_fma_f32 v[138:139], v[140:141], v[138:139], v[138:139]
	v_pk_fma_f32 v[150:151], v[152:153], v[150:151], v[150:151]
	v_div_scale_f32 v142, s[28:29], v38, v134, v38
	v_div_scale_f32 v143, s[30:31], v39, v135, v39
	v_div_scale_f32 v154, s[2:3], v4, v146, v4
	v_div_scale_f32 v155, s[100:101], v5, v147, v5
	v_pk_mul_f32 v[144:145], v[142:143], v[138:139]
	v_pk_mul_f32 v[156:157], v[154:155], v[150:151]
	v_pk_fma_f32 v[140:141], v[136:137], v[144:145], v[142:143] neg_lo:[1,0,0] neg_hi:[1,0,0]
	v_pk_fma_f32 v[152:153], v[148:149], v[156:157], v[154:155] neg_lo:[1,0,0] neg_hi:[1,0,0]
	v_pk_fma_f32 v[144:145], v[140:141], v[138:139], v[144:145]
	v_pk_fma_f32 v[156:157], v[152:153], v[150:151], v[156:157]
	v_pk_fma_f32 v[136:137], v[136:137], v[144:145], v[142:143] neg_lo:[1,0,0] neg_hi:[1,0,0]
	v_pk_fma_f32 v[148:149], v[148:149], v[156:157], v[154:155] neg_lo:[1,0,0] neg_hi:[1,0,0]
	s_mov_b64 vcc, s[28:29]
	v_div_fmas_f32 v136, v136, v138, v144
	s_mov_b64 vcc, s[30:31]
	v_div_fmas_f32 v137, v137, v139, v145
	s_mov_b64 vcc, s[2:3]
	v_div_fmas_f32 v148, v148, v150, v156
	s_mov_b64 vcc, s[100:101]
	v_div_fmas_f32 v149, v149, v151, v157
	v_div_fixup_f32 v134, v136, v134, v38
	v_div_fixup_f32 v135, v137, v135, v39
	v_div_fixup_f32 v146, v148, v146, v4
	v_div_fixup_f32 v147, v149, v147, v5
	v_cvt_pk_bf16_f32 v136, v134, v135
	v_cvt_pk_bf16_f32 v148, v146, v147
	ds_write_b16 v159, v136 offset:2304
	ds_write_b16_d16_hi v159, v136 offset:2576
	ds_write_b16 v159, v148 offset:2368
	ds_write_b16_d16_hi v159, v148 offset:2640
	v_mul_f32_e32 v134, 0xbfb8aa3b, v56
	v_mul_f32_e32 v135, 0xbfb8aa3b, v57
	v_mul_f32_e32 v146, 0xbfb8aa3b, v22
	v_mul_f32_e32 v147, 0xbfb8aa3b, v23
	v_exp_f32_e32 v134, v134
	v_exp_f32_e32 v135, v135
	v_exp_f32_e32 v146, v146
	v_exp_f32_e32 v147, v147
	v_pk_add_f32 v[134:135], v[134:135], 1.0 op_sel_hi:[1,0]
	v_pk_add_f32 v[146:147], v[146:147], 1.0 op_sel_hi:[1,0]
	v_div_scale_f32 v136, vcc, v134, v134, v56
	v_div_scale_f32 v137, vcc, v135, v135, v57
	v_div_scale_f32 v148, vcc, v146, v146, v22
	v_div_scale_f32 v149, vcc, v147, v147, v23
	v_rcp_f32_e32 v138, v136
	v_rcp_f32_e32 v139, v137
	v_rcp_f32_e32 v150, v148
	v_rcp_f32_e32 v151, v149
	v_pk_fma_f32 v[140:141], v[136:137], v[138:139], 1.0 op_sel_hi:[1,1,0] neg_lo:[1,0,0] neg_hi:[1,0,0]
	v_pk_fma_f32 v[152:153], v[148:149], v[150:151], 1.0 op_sel_hi:[1,1,0] neg_lo:[1,0,0] neg_hi:[1,0,0]
	v_pk_fma_f32 v[138:139], v[140:141], v[138:139], v[138:139]
	v_pk_fma_f32 v[150:151], v[152:153], v[150:151], v[150:151]
	v_div_scale_f32 v142, s[28:29], v56, v134, v56
	v_div_scale_f32 v143, s[30:31], v57, v135, v57
	v_div_scale_f32 v154, s[2:3], v22, v146, v22
	v_div_scale_f32 v155, s[100:101], v23, v147, v23
	v_pk_mul_f32 v[144:145], v[142:143], v[138:139]
	v_pk_mul_f32 v[156:157], v[154:155], v[150:151]
	v_pk_fma_f32 v[140:141], v[136:137], v[144:145], v[142:143] neg_lo:[1,0,0] neg_hi:[1,0,0]
	v_pk_fma_f32 v[152:153], v[148:149], v[156:157], v[154:155] neg_lo:[1,0,0] neg_hi:[1,0,0]
	v_pk_fma_f32 v[144:145], v[140:141], v[138:139], v[144:145]
	v_pk_fma_f32 v[156:157], v[152:153], v[150:151], v[156:157]
	v_pk_fma_f32 v[136:137], v[136:137], v[144:145], v[142:143] neg_lo:[1,0,0] neg_hi:[1,0,0]
	v_pk_fma_f32 v[148:149], v[148:149], v[156:157], v[154:155] neg_lo:[1,0,0] neg_hi:[1,0,0]
	s_mov_b64 vcc, s[28:29]
	v_div_fmas_f32 v136, v136, v138, v144
	s_mov_b64 vcc, s[30:31]
	v_div_fmas_f32 v137, v137, v139, v145
	s_mov_b64 vcc, s[2:3]
	v_div_fmas_f32 v148, v148, v150, v156
	s_mov_b64 vcc, s[100:101]
	v_div_fmas_f32 v149, v149, v151, v157
	v_div_fixup_f32 v134, v136, v134, v56
	v_div_fixup_f32 v135, v137, v135, v57
	v_div_fixup_f32 v146, v148, v146, v22
	v_div_fixup_f32 v147, v149, v147, v23
	v_cvt_pk_bf16_f32 v136, v134, v135
	v_cvt_pk_bf16_f32 v148, v146, v147
	ds_write_b16 v159, v136 offset:2720
	ds_write_b16_d16_hi v159, v136 offset:2992
	ds_write_b16 v159, v148 offset:2784
	ds_write_b16_d16_hi v159, v148 offset:3056
	v_mul_f32_e32 v134, 0xbfb8aa3b, v40
	v_mul_f32_e32 v135, 0xbfb8aa3b, v41
	v_mul_f32_e32 v146, 0xbfb8aa3b, v6
	v_mul_f32_e32 v147, 0xbfb8aa3b, v7
	v_exp_f32_e32 v134, v134
	v_exp_f32_e32 v135, v135
	v_exp_f32_e32 v146, v146
	v_exp_f32_e32 v147, v147
	v_pk_add_f32 v[134:135], v[134:135], 1.0 op_sel_hi:[1,0]
	v_pk_add_f32 v[146:147], v[146:147], 1.0 op_sel_hi:[1,0]
	v_div_scale_f32 v136, vcc, v134, v134, v40
	v_div_scale_f32 v137, vcc, v135, v135, v41
	v_div_scale_f32 v148, vcc, v146, v146, v6
	v_div_scale_f32 v149, vcc, v147, v147, v7
	v_rcp_f32_e32 v138, v136
	v_rcp_f32_e32 v139, v137
	v_rcp_f32_e32 v150, v148
	v_rcp_f32_e32 v151, v149
	v_pk_fma_f32 v[140:141], v[136:137], v[138:139], 1.0 op_sel_hi:[1,1,0] neg_lo:[1,0,0] neg_hi:[1,0,0]
	v_pk_fma_f32 v[152:153], v[148:149], v[150:151], 1.0 op_sel_hi:[1,1,0] neg_lo:[1,0,0] neg_hi:[1,0,0]
	v_pk_fma_f32 v[138:139], v[140:141], v[138:139], v[138:139]
	v_pk_fma_f32 v[150:151], v[152:153], v[150:151], v[150:151]
	v_div_scale_f32 v142, s[28:29], v40, v134, v40
	v_div_scale_f32 v143, s[30:31], v41, v135, v41
	v_div_scale_f32 v154, s[2:3], v6, v146, v6
	v_div_scale_f32 v155, s[100:101], v7, v147, v7
	v_pk_mul_f32 v[144:145], v[142:143], v[138:139]
	v_pk_mul_f32 v[156:157], v[154:155], v[150:151]
	v_pk_fma_f32 v[140:141], v[136:137], v[144:145], v[142:143] neg_lo:[1,0,0] neg_hi:[1,0,0]
	v_pk_fma_f32 v[152:153], v[148:149], v[156:157], v[154:155] neg_lo:[1,0,0] neg_hi:[1,0,0]
	v_pk_fma_f32 v[144:145], v[140:141], v[138:139], v[144:145]
	v_pk_fma_f32 v[156:157], v[152:153], v[150:151], v[156:157]
	v_pk_fma_f32 v[136:137], v[136:137], v[144:145], v[142:143] neg_lo:[1,0,0] neg_hi:[1,0,0]
	v_pk_fma_f32 v[148:149], v[148:149], v[156:157], v[154:155] neg_lo:[1,0,0] neg_hi:[1,0,0]
	s_mov_b64 vcc, s[28:29]
	v_div_fmas_f32 v136, v136, v138, v144
	s_mov_b64 vcc, s[30:31]
	v_div_fmas_f32 v137, v137, v139, v145
	s_mov_b64 vcc, s[2:3]
	v_div_fmas_f32 v148, v148, v150, v156
	s_mov_b64 vcc, s[100:101]
	v_div_fmas_f32 v149, v149, v151, v157
	v_div_fixup_f32 v134, v136, v134, v40
	v_div_fixup_f32 v135, v137, v135, v41
	v_div_fixup_f32 v146, v148, v146, v6
	v_div_fixup_f32 v147, v149, v147, v7
	v_cvt_pk_bf16_f32 v136, v134, v135
	v_cvt_pk_bf16_f32 v148, v146, v147
	ds_write_b16 v159, v136 offset:2848
	ds_write_b16_d16_hi v159, v136 offset:3120
	ds_write_b16 v159, v148 offset:2912
	ds_write_b16_d16_hi v159, v148 offset:3184
	v_mul_f32_e32 v134, 0xbfb8aa3b, v58
	v_mul_f32_e32 v135, 0xbfb8aa3b, v59
	v_mul_f32_e32 v146, 0xbfb8aa3b, v24
	v_mul_f32_e32 v147, 0xbfb8aa3b, v25
	v_exp_f32_e32 v134, v134
	v_exp_f32_e32 v135, v135
	v_exp_f32_e32 v146, v146
	v_exp_f32_e32 v147, v147
	v_pk_add_f32 v[134:135], v[134:135], 1.0 op_sel_hi:[1,0]
	v_pk_add_f32 v[146:147], v[146:147], 1.0 op_sel_hi:[1,0]
	v_div_scale_f32 v136, vcc, v134, v134, v58
	v_div_scale_f32 v137, vcc, v135, v135, v59
	v_div_scale_f32 v148, vcc, v146, v146, v24
	v_div_scale_f32 v149, vcc, v147, v147, v25
	v_rcp_f32_e32 v138, v136
	v_rcp_f32_e32 v139, v137
	v_rcp_f32_e32 v150, v148
	v_rcp_f32_e32 v151, v149
	v_pk_fma_f32 v[140:141], v[136:137], v[138:139], 1.0 op_sel_hi:[1,1,0] neg_lo:[1,0,0] neg_hi:[1,0,0]
	v_pk_fma_f32 v[152:153], v[148:149], v[150:151], 1.0 op_sel_hi:[1,1,0] neg_lo:[1,0,0] neg_hi:[1,0,0]
	v_pk_fma_f32 v[138:139], v[140:141], v[138:139], v[138:139]
	v_pk_fma_f32 v[150:151], v[152:153], v[150:151], v[150:151]
	v_div_scale_f32 v142, s[28:29], v58, v134, v58
	v_div_scale_f32 v143, s[30:31], v59, v135, v59
	v_div_scale_f32 v154, s[2:3], v24, v146, v24
	v_div_scale_f32 v155, s[100:101], v25, v147, v25
	v_pk_mul_f32 v[144:145], v[142:143], v[138:139]
	v_pk_mul_f32 v[156:157], v[154:155], v[150:151]
	v_pk_fma_f32 v[140:141], v[136:137], v[144:145], v[142:143] neg_lo:[1,0,0] neg_hi:[1,0,0]
	v_pk_fma_f32 v[152:153], v[148:149], v[156:157], v[154:155] neg_lo:[1,0,0] neg_hi:[1,0,0]
	v_pk_fma_f32 v[144:145], v[140:141], v[138:139], v[144:145]
	v_pk_fma_f32 v[156:157], v[152:153], v[150:151], v[156:157]
	v_pk_fma_f32 v[136:137], v[136:137], v[144:145], v[142:143] neg_lo:[1,0,0] neg_hi:[1,0,0]
	v_pk_fma_f32 v[148:149], v[148:149], v[156:157], v[154:155] neg_lo:[1,0,0] neg_hi:[1,0,0]
	s_mov_b64 vcc, s[28:29]
	v_div_fmas_f32 v136, v136, v138, v144
	s_mov_b64 vcc, s[30:31]
	v_div_fmas_f32 v137, v137, v139, v145
	s_mov_b64 vcc, s[2:3]
	v_div_fmas_f32 v148, v148, v150, v156
	s_mov_b64 vcc, s[100:101]
	v_div_fmas_f32 v149, v149, v151, v157
	v_div_fixup_f32 v134, v136, v134, v58
	v_div_fixup_f32 v135, v137, v135, v59
	v_div_fixup_f32 v146, v148, v146, v24
	v_div_fixup_f32 v147, v149, v147, v25
	v_cvt_pk_bf16_f32 v136, v134, v135
	v_cvt_pk_bf16_f32 v148, v146, v147
	ds_write_b16 v159, v136 offset:4352
	ds_write_b16_d16_hi v159, v136 offset:4624
	ds_write_b16 v159, v148 offset:4416
	ds_write_b16_d16_hi v159, v148 offset:4688
	v_mul_f32_e32 v134, 0xbfb8aa3b, v42
	v_mul_f32_e32 v135, 0xbfb8aa3b, v43
	v_mul_f32_e32 v146, 0xbfb8aa3b, v8
	v_mul_f32_e32 v147, 0xbfb8aa3b, v9
	v_exp_f32_e32 v134, v134
	v_exp_f32_e32 v135, v135
	v_exp_f32_e32 v146, v146
	v_exp_f32_e32 v147, v147
	v_pk_add_f32 v[134:135], v[134:135], 1.0 op_sel_hi:[1,0]
	v_pk_add_f32 v[146:147], v[146:147], 1.0 op_sel_hi:[1,0]
	v_div_scale_f32 v136, vcc, v134, v134, v42
	v_div_scale_f32 v137, vcc, v135, v135, v43
	v_div_scale_f32 v148, vcc, v146, v146, v8
	v_div_scale_f32 v149, vcc, v147, v147, v9
	v_rcp_f32_e32 v138, v136
	v_rcp_f32_e32 v139, v137
	v_rcp_f32_e32 v150, v148
	v_rcp_f32_e32 v151, v149
	v_pk_fma_f32 v[140:141], v[136:137], v[138:139], 1.0 op_sel_hi:[1,1,0] neg_lo:[1,0,0] neg_hi:[1,0,0]
	v_pk_fma_f32 v[152:153], v[148:149], v[150:151], 1.0 op_sel_hi:[1,1,0] neg_lo:[1,0,0] neg_hi:[1,0,0]
	v_pk_fma_f32 v[138:139], v[140:141], v[138:139], v[138:139]
	v_pk_fma_f32 v[150:151], v[152:153], v[150:151], v[150:151]
	v_div_scale_f32 v142, s[28:29], v42, v134, v42
	v_div_scale_f32 v143, s[30:31], v43, v135, v43
	v_div_scale_f32 v154, s[2:3], v8, v146, v8
	v_div_scale_f32 v155, s[100:101], v9, v147, v9
	v_pk_mul_f32 v[144:145], v[142:143], v[138:139]
	v_pk_mul_f32 v[156:157], v[154:155], v[150:151]
	v_pk_fma_f32 v[140:141], v[136:137], v[144:145], v[142:143] neg_lo:[1,0,0] neg_hi:[1,0,0]
	v_pk_fma_f32 v[152:153], v[148:149], v[156:157], v[154:155] neg_lo:[1,0,0] neg_hi:[1,0,0]
	v_pk_fma_f32 v[144:145], v[140:141], v[138:139], v[144:145]
	v_pk_fma_f32 v[156:157], v[152:153], v[150:151], v[156:157]
	v_pk_fma_f32 v[136:137], v[136:137], v[144:145], v[142:143] neg_lo:[1,0,0] neg_hi:[1,0,0]
	v_pk_fma_f32 v[148:149], v[148:149], v[156:157], v[154:155] neg_lo:[1,0,0] neg_hi:[1,0,0]
	s_mov_b64 vcc, s[28:29]
	v_div_fmas_f32 v136, v136, v138, v144
	s_mov_b64 vcc, s[30:31]
	v_div_fmas_f32 v137, v137, v139, v145
	s_mov_b64 vcc, s[2:3]
	v_div_fmas_f32 v148, v148, v150, v156
	s_mov_b64 vcc, s[100:101]
	v_div_fmas_f32 v149, v149, v151, v157
	v_div_fixup_f32 v134, v136, v134, v42
	v_div_fixup_f32 v135, v137, v135, v43
	v_div_fixup_f32 v146, v148, v146, v8
	v_div_fixup_f32 v147, v149, v147, v9
	v_cvt_pk_bf16_f32 v136, v134, v135
	v_cvt_pk_bf16_f32 v148, v146, v147
	ds_write_b16 v159, v136 offset:4480
	ds_write_b16_d16_hi v159, v136 offset:4752
	ds_write_b16 v159, v148 offset:4544
	ds_write_b16_d16_hi v159, v148 offset:4816
	v_mul_f32_e32 v134, 0xbfb8aa3b, v60
	v_mul_f32_e32 v135, 0xbfb8aa3b, v61
	v_mul_f32_e32 v146, 0xbfb8aa3b, v26
	v_mul_f32_e32 v147, 0xbfb8aa3b, v27
	v_exp_f32_e32 v134, v134
	v_exp_f32_e32 v135, v135
	v_exp_f32_e32 v146, v146
	v_exp_f32_e32 v147, v147
	v_pk_add_f32 v[134:135], v[134:135], 1.0 op_sel_hi:[1,0]
	v_pk_add_f32 v[146:147], v[146:147], 1.0 op_sel_hi:[1,0]
	v_div_scale_f32 v136, vcc, v134, v134, v60
	v_div_scale_f32 v137, vcc, v135, v135, v61
	v_div_scale_f32 v148, vcc, v146, v146, v26
	v_div_scale_f32 v149, vcc, v147, v147, v27
	v_rcp_f32_e32 v138, v136
	v_rcp_f32_e32 v139, v137
	v_rcp_f32_e32 v150, v148
	v_rcp_f32_e32 v151, v149
	v_pk_fma_f32 v[140:141], v[136:137], v[138:139], 1.0 op_sel_hi:[1,1,0] neg_lo:[1,0,0] neg_hi:[1,0,0]
	v_pk_fma_f32 v[152:153], v[148:149], v[150:151], 1.0 op_sel_hi:[1,1,0] neg_lo:[1,0,0] neg_hi:[1,0,0]
	v_pk_fma_f32 v[138:139], v[140:141], v[138:139], v[138:139]
	v_pk_fma_f32 v[150:151], v[152:153], v[150:151], v[150:151]
	v_div_scale_f32 v142, s[28:29], v60, v134, v60
	v_div_scale_f32 v143, s[30:31], v61, v135, v61
	v_div_scale_f32 v154, s[2:3], v26, v146, v26
	v_div_scale_f32 v155, s[100:101], v27, v147, v27
	v_pk_mul_f32 v[144:145], v[142:143], v[138:139]
	v_pk_mul_f32 v[156:157], v[154:155], v[150:151]
	v_pk_fma_f32 v[140:141], v[136:137], v[144:145], v[142:143] neg_lo:[1,0,0] neg_hi:[1,0,0]
	v_pk_fma_f32 v[152:153], v[148:149], v[156:157], v[154:155] neg_lo:[1,0,0] neg_hi:[1,0,0]
	v_pk_fma_f32 v[144:145], v[140:141], v[138:139], v[144:145]
	v_pk_fma_f32 v[156:157], v[152:153], v[150:151], v[156:157]
	v_pk_fma_f32 v[136:137], v[136:137], v[144:145], v[142:143] neg_lo:[1,0,0] neg_hi:[1,0,0]
	v_pk_fma_f32 v[148:149], v[148:149], v[156:157], v[154:155] neg_lo:[1,0,0] neg_hi:[1,0,0]
	s_mov_b64 vcc, s[28:29]
	v_div_fmas_f32 v136, v136, v138, v144
	s_mov_b64 vcc, s[30:31]
	v_div_fmas_f32 v137, v137, v139, v145
	s_mov_b64 vcc, s[2:3]
	v_div_fmas_f32 v148, v148, v150, v156
	s_mov_b64 vcc, s[100:101]
	v_div_fmas_f32 v149, v149, v151, v157
	v_div_fixup_f32 v134, v136, v134, v60
	v_div_fixup_f32 v135, v137, v135, v61
	v_div_fixup_f32 v146, v148, v146, v26
	v_div_fixup_f32 v147, v149, v147, v27
	v_cvt_pk_bf16_f32 v136, v134, v135
	v_cvt_pk_bf16_f32 v148, v146, v147
	ds_write_b16 v159, v136 offset:4896
	ds_write_b16_d16_hi v159, v136 offset:5168
	ds_write_b16 v159, v148 offset:4960
	ds_write_b16_d16_hi v159, v148 offset:5232
	v_mul_f32_e32 v134, 0xbfb8aa3b, v44
	v_mul_f32_e32 v135, 0xbfb8aa3b, v45
	v_mul_f32_e32 v146, 0xbfb8aa3b, v10
	v_mul_f32_e32 v147, 0xbfb8aa3b, v11
	v_exp_f32_e32 v134, v134
	v_exp_f32_e32 v135, v135
	v_exp_f32_e32 v146, v146
	v_exp_f32_e32 v147, v147
	v_pk_add_f32 v[134:135], v[134:135], 1.0 op_sel_hi:[1,0]
	v_pk_add_f32 v[146:147], v[146:147], 1.0 op_sel_hi:[1,0]
	v_div_scale_f32 v136, vcc, v134, v134, v44
	v_div_scale_f32 v137, vcc, v135, v135, v45
	v_div_scale_f32 v148, vcc, v146, v146, v10
	v_div_scale_f32 v149, vcc, v147, v147, v11
	v_rcp_f32_e32 v138, v136
	v_rcp_f32_e32 v139, v137
	v_rcp_f32_e32 v150, v148
	v_rcp_f32_e32 v151, v149
	v_pk_fma_f32 v[140:141], v[136:137], v[138:139], 1.0 op_sel_hi:[1,1,0] neg_lo:[1,0,0] neg_hi:[1,0,0]
	v_pk_fma_f32 v[152:153], v[148:149], v[150:151], 1.0 op_sel_hi:[1,1,0] neg_lo:[1,0,0] neg_hi:[1,0,0]
	v_pk_fma_f32 v[138:139], v[140:141], v[138:139], v[138:139]
	v_pk_fma_f32 v[150:151], v[152:153], v[150:151], v[150:151]
	v_div_scale_f32 v142, s[28:29], v44, v134, v44
	v_div_scale_f32 v143, s[30:31], v45, v135, v45
	v_div_scale_f32 v154, s[2:3], v10, v146, v10
	v_div_scale_f32 v155, s[100:101], v11, v147, v11
	v_pk_mul_f32 v[144:145], v[142:143], v[138:139]
	v_pk_mul_f32 v[156:157], v[154:155], v[150:151]
	v_pk_fma_f32 v[140:141], v[136:137], v[144:145], v[142:143] neg_lo:[1,0,0] neg_hi:[1,0,0]
	v_pk_fma_f32 v[152:153], v[148:149], v[156:157], v[154:155] neg_lo:[1,0,0] neg_hi:[1,0,0]
	v_pk_fma_f32 v[144:145], v[140:141], v[138:139], v[144:145]
	v_pk_fma_f32 v[156:157], v[152:153], v[150:151], v[156:157]
	v_pk_fma_f32 v[136:137], v[136:137], v[144:145], v[142:143] neg_lo:[1,0,0] neg_hi:[1,0,0]
	v_pk_fma_f32 v[148:149], v[148:149], v[156:157], v[154:155] neg_lo:[1,0,0] neg_hi:[1,0,0]
	s_mov_b64 vcc, s[28:29]
	v_div_fmas_f32 v136, v136, v138, v144
	s_mov_b64 vcc, s[30:31]
	v_div_fmas_f32 v137, v137, v139, v145
	s_mov_b64 vcc, s[2:3]
	v_div_fmas_f32 v148, v148, v150, v156
	s_mov_b64 vcc, s[100:101]
	v_div_fmas_f32 v149, v149, v151, v157
	v_div_fixup_f32 v134, v136, v134, v44
	v_div_fixup_f32 v135, v137, v135, v45
	v_div_fixup_f32 v146, v148, v146, v10
	v_div_fixup_f32 v147, v149, v147, v11
	v_cvt_pk_bf16_f32 v136, v134, v135
	v_cvt_pk_bf16_f32 v148, v146, v147
	ds_write_b16 v159, v136 offset:5024
	ds_write_b16_d16_hi v159, v136 offset:5296
	ds_write_b16 v159, v148 offset:5088
	ds_write_b16_d16_hi v159, v148 offset:5360
	v_mul_f32_e32 v134, 0xbfb8aa3b, v62
	v_mul_f32_e32 v135, 0xbfb8aa3b, v63
	v_mul_f32_e32 v146, 0xbfb8aa3b, v28
	v_mul_f32_e32 v147, 0xbfb8aa3b, v29
	v_exp_f32_e32 v134, v134
	v_exp_f32_e32 v135, v135
	v_exp_f32_e32 v146, v146
	v_exp_f32_e32 v147, v147
	v_pk_add_f32 v[134:135], v[134:135], 1.0 op_sel_hi:[1,0]
	v_pk_add_f32 v[146:147], v[146:147], 1.0 op_sel_hi:[1,0]
	v_div_scale_f32 v136, vcc, v134, v134, v62
	v_div_scale_f32 v137, vcc, v135, v135, v63
	v_div_scale_f32 v148, vcc, v146, v146, v28
	v_div_scale_f32 v149, vcc, v147, v147, v29
	v_rcp_f32_e32 v138, v136
	v_rcp_f32_e32 v139, v137
	v_rcp_f32_e32 v150, v148
	v_rcp_f32_e32 v151, v149
	v_pk_fma_f32 v[140:141], v[136:137], v[138:139], 1.0 op_sel_hi:[1,1,0] neg_lo:[1,0,0] neg_hi:[1,0,0]
	v_pk_fma_f32 v[152:153], v[148:149], v[150:151], 1.0 op_sel_hi:[1,1,0] neg_lo:[1,0,0] neg_hi:[1,0,0]
	v_pk_fma_f32 v[138:139], v[140:141], v[138:139], v[138:139]
	v_pk_fma_f32 v[150:151], v[152:153], v[150:151], v[150:151]
	v_div_scale_f32 v142, s[28:29], v62, v134, v62
	v_div_scale_f32 v143, s[30:31], v63, v135, v63
	v_div_scale_f32 v154, s[2:3], v28, v146, v28
	v_div_scale_f32 v155, s[100:101], v29, v147, v29
	v_pk_mul_f32 v[144:145], v[142:143], v[138:139]
	v_pk_mul_f32 v[156:157], v[154:155], v[150:151]
	v_pk_fma_f32 v[140:141], v[136:137], v[144:145], v[142:143] neg_lo:[1,0,0] neg_hi:[1,0,0]
	v_pk_fma_f32 v[152:153], v[148:149], v[156:157], v[154:155] neg_lo:[1,0,0] neg_hi:[1,0,0]
	v_pk_fma_f32 v[144:145], v[140:141], v[138:139], v[144:145]
	v_pk_fma_f32 v[156:157], v[152:153], v[150:151], v[156:157]
	v_pk_fma_f32 v[136:137], v[136:137], v[144:145], v[142:143] neg_lo:[1,0,0] neg_hi:[1,0,0]
	v_pk_fma_f32 v[148:149], v[148:149], v[156:157], v[154:155] neg_lo:[1,0,0] neg_hi:[1,0,0]
	s_mov_b64 vcc, s[28:29]
	v_div_fmas_f32 v136, v136, v138, v144
	s_mov_b64 vcc, s[30:31]
	v_div_fmas_f32 v137, v137, v139, v145
	s_mov_b64 vcc, s[2:3]
	v_div_fmas_f32 v148, v148, v150, v156
	s_mov_b64 vcc, s[100:101]
	v_div_fmas_f32 v149, v149, v151, v157
	v_div_fixup_f32 v134, v136, v134, v62
	v_div_fixup_f32 v135, v137, v135, v63
	v_div_fixup_f32 v146, v148, v146, v28
	v_div_fixup_f32 v147, v149, v147, v29
	v_cvt_pk_bf16_f32 v136, v134, v135
	v_cvt_pk_bf16_f32 v148, v146, v147
	ds_write_b16 v159, v136 offset:6528
	ds_write_b16_d16_hi v159, v136 offset:6800
	ds_write_b16 v159, v148 offset:6592
	ds_write_b16_d16_hi v159, v148 offset:6864
	v_mul_f32_e32 v134, 0xbfb8aa3b, v46
	v_mul_f32_e32 v135, 0xbfb8aa3b, v47
	v_mul_f32_e32 v146, 0xbfb8aa3b, v12
	v_mul_f32_e32 v147, 0xbfb8aa3b, v13
	v_exp_f32_e32 v134, v134
	v_exp_f32_e32 v135, v135
	v_exp_f32_e32 v146, v146
	v_exp_f32_e32 v147, v147
	v_pk_add_f32 v[134:135], v[134:135], 1.0 op_sel_hi:[1,0]
	v_pk_add_f32 v[146:147], v[146:147], 1.0 op_sel_hi:[1,0]
	v_div_scale_f32 v136, vcc, v134, v134, v46
	v_div_scale_f32 v137, vcc, v135, v135, v47
	v_div_scale_f32 v148, vcc, v146, v146, v12
	v_div_scale_f32 v149, vcc, v147, v147, v13
	v_rcp_f32_e32 v138, v136
	v_rcp_f32_e32 v139, v137
	v_rcp_f32_e32 v150, v148
	v_rcp_f32_e32 v151, v149
	v_pk_fma_f32 v[140:141], v[136:137], v[138:139], 1.0 op_sel_hi:[1,1,0] neg_lo:[1,0,0] neg_hi:[1,0,0]
	v_pk_fma_f32 v[152:153], v[148:149], v[150:151], 1.0 op_sel_hi:[1,1,0] neg_lo:[1,0,0] neg_hi:[1,0,0]
	v_pk_fma_f32 v[138:139], v[140:141], v[138:139], v[138:139]
	v_pk_fma_f32 v[150:151], v[152:153], v[150:151], v[150:151]
	v_div_scale_f32 v142, s[28:29], v46, v134, v46
	v_div_scale_f32 v143, s[30:31], v47, v135, v47
	v_div_scale_f32 v154, s[2:3], v12, v146, v12
	v_div_scale_f32 v155, s[100:101], v13, v147, v13
	v_pk_mul_f32 v[144:145], v[142:143], v[138:139]
	v_pk_mul_f32 v[156:157], v[154:155], v[150:151]
	v_pk_fma_f32 v[140:141], v[136:137], v[144:145], v[142:143] neg_lo:[1,0,0] neg_hi:[1,0,0]
	v_pk_fma_f32 v[152:153], v[148:149], v[156:157], v[154:155] neg_lo:[1,0,0] neg_hi:[1,0,0]
	v_pk_fma_f32 v[144:145], v[140:141], v[138:139], v[144:145]
	v_pk_fma_f32 v[156:157], v[152:153], v[150:151], v[156:157]
	v_pk_fma_f32 v[136:137], v[136:137], v[144:145], v[142:143] neg_lo:[1,0,0] neg_hi:[1,0,0]
	v_pk_fma_f32 v[148:149], v[148:149], v[156:157], v[154:155] neg_lo:[1,0,0] neg_hi:[1,0,0]
	s_mov_b64 vcc, s[28:29]
	v_div_fmas_f32 v136, v136, v138, v144
	s_mov_b64 vcc, s[30:31]
	v_div_fmas_f32 v137, v137, v139, v145
	s_mov_b64 vcc, s[2:3]
	v_div_fmas_f32 v148, v148, v150, v156
	s_mov_b64 vcc, s[100:101]
	v_div_fmas_f32 v149, v149, v151, v157
	v_div_fixup_f32 v134, v136, v134, v46
	v_div_fixup_f32 v135, v137, v135, v47
	v_div_fixup_f32 v146, v148, v146, v12
	v_div_fixup_f32 v147, v149, v147, v13
	v_cvt_pk_bf16_f32 v136, v134, v135
	v_cvt_pk_bf16_f32 v148, v146, v147
	ds_write_b16 v159, v136 offset:6656
	ds_write_b16_d16_hi v159, v136 offset:6928
	ds_write_b16 v159, v148 offset:6720
	ds_write_b16_d16_hi v159, v148 offset:6992
	v_mul_f32_e32 v134, 0xbfb8aa3b, v64
	v_mul_f32_e32 v135, 0xbfb8aa3b, v65
	v_mul_f32_e32 v146, 0xbfb8aa3b, v30
	v_mul_f32_e32 v147, 0xbfb8aa3b, v31
	v_exp_f32_e32 v134, v134
	v_exp_f32_e32 v135, v135
	v_exp_f32_e32 v146, v146
	v_exp_f32_e32 v147, v147
	v_pk_add_f32 v[134:135], v[134:135], 1.0 op_sel_hi:[1,0]
	v_pk_add_f32 v[146:147], v[146:147], 1.0 op_sel_hi:[1,0]
	v_div_scale_f32 v136, vcc, v134, v134, v64
	v_div_scale_f32 v137, vcc, v135, v135, v65
	v_div_scale_f32 v148, vcc, v146, v146, v30
	v_div_scale_f32 v149, vcc, v147, v147, v31
	v_rcp_f32_e32 v138, v136
	v_rcp_f32_e32 v139, v137
	v_rcp_f32_e32 v150, v148
	v_rcp_f32_e32 v151, v149
	v_pk_fma_f32 v[140:141], v[136:137], v[138:139], 1.0 op_sel_hi:[1,1,0] neg_lo:[1,0,0] neg_hi:[1,0,0]
	v_pk_fma_f32 v[152:153], v[148:149], v[150:151], 1.0 op_sel_hi:[1,1,0] neg_lo:[1,0,0] neg_hi:[1,0,0]
	v_pk_fma_f32 v[138:139], v[140:141], v[138:139], v[138:139]
	v_pk_fma_f32 v[150:151], v[152:153], v[150:151], v[150:151]
	v_div_scale_f32 v142, s[28:29], v64, v134, v64
	v_div_scale_f32 v143, s[30:31], v65, v135, v65
	v_div_scale_f32 v154, s[2:3], v30, v146, v30
	v_div_scale_f32 v155, s[100:101], v31, v147, v31
	v_pk_mul_f32 v[144:145], v[142:143], v[138:139]
	v_pk_mul_f32 v[156:157], v[154:155], v[150:151]
	v_pk_fma_f32 v[140:141], v[136:137], v[144:145], v[142:143] neg_lo:[1,0,0] neg_hi:[1,0,0]
	v_pk_fma_f32 v[152:153], v[148:149], v[156:157], v[154:155] neg_lo:[1,0,0] neg_hi:[1,0,0]
	v_pk_fma_f32 v[144:145], v[140:141], v[138:139], v[144:145]
	v_pk_fma_f32 v[156:157], v[152:153], v[150:151], v[156:157]
	v_pk_fma_f32 v[136:137], v[136:137], v[144:145], v[142:143] neg_lo:[1,0,0] neg_hi:[1,0,0]
	v_pk_fma_f32 v[148:149], v[148:149], v[156:157], v[154:155] neg_lo:[1,0,0] neg_hi:[1,0,0]
	s_mov_b64 vcc, s[28:29]
	v_div_fmas_f32 v136, v136, v138, v144
	s_mov_b64 vcc, s[30:31]
	v_div_fmas_f32 v137, v137, v139, v145
	s_mov_b64 vcc, s[2:3]
	v_div_fmas_f32 v148, v148, v150, v156
	s_mov_b64 vcc, s[100:101]
	v_div_fmas_f32 v149, v149, v151, v157
	v_div_fixup_f32 v134, v136, v134, v64
	v_div_fixup_f32 v135, v137, v135, v65
	v_div_fixup_f32 v146, v148, v146, v30
	v_div_fixup_f32 v147, v149, v147, v31
	v_cvt_pk_bf16_f32 v136, v134, v135
	v_cvt_pk_bf16_f32 v148, v146, v147
	ds_write_b16 v159, v136 offset:7072
	ds_write_b16_d16_hi v159, v136 offset:7344
	ds_write_b16 v159, v148 offset:7136
	ds_write_b16_d16_hi v159, v148 offset:7408
	v_mul_f32_e32 v134, 0xbfb8aa3b, v48
	v_mul_f32_e32 v135, 0xbfb8aa3b, v49
	v_mul_f32_e32 v146, 0xbfb8aa3b, v14
	v_mul_f32_e32 v147, 0xbfb8aa3b, v15
	v_exp_f32_e32 v134, v134
	v_exp_f32_e32 v135, v135
	v_exp_f32_e32 v146, v146
	v_exp_f32_e32 v147, v147
	v_pk_add_f32 v[134:135], v[134:135], 1.0 op_sel_hi:[1,0]
	v_pk_add_f32 v[146:147], v[146:147], 1.0 op_sel_hi:[1,0]
	v_div_scale_f32 v136, vcc, v134, v134, v48
	v_div_scale_f32 v137, vcc, v135, v135, v49
	v_div_scale_f32 v148, vcc, v146, v146, v14
	v_div_scale_f32 v149, vcc, v147, v147, v15
	v_rcp_f32_e32 v138, v136
	v_rcp_f32_e32 v139, v137
	v_rcp_f32_e32 v150, v148
	v_rcp_f32_e32 v151, v149
	v_pk_fma_f32 v[140:141], v[136:137], v[138:139], 1.0 op_sel_hi:[1,1,0] neg_lo:[1,0,0] neg_hi:[1,0,0]
	v_pk_fma_f32 v[152:153], v[148:149], v[150:151], 1.0 op_sel_hi:[1,1,0] neg_lo:[1,0,0] neg_hi:[1,0,0]
	v_pk_fma_f32 v[138:139], v[140:141], v[138:139], v[138:139]
	v_pk_fma_f32 v[150:151], v[152:153], v[150:151], v[150:151]
	v_div_scale_f32 v142, s[28:29], v48, v134, v48
	v_div_scale_f32 v143, s[30:31], v49, v135, v49
	v_div_scale_f32 v154, s[2:3], v14, v146, v14
	v_div_scale_f32 v155, s[100:101], v15, v147, v15
	v_pk_mul_f32 v[144:145], v[142:143], v[138:139]
	v_pk_mul_f32 v[156:157], v[154:155], v[150:151]
	v_pk_fma_f32 v[140:141], v[136:137], v[144:145], v[142:143] neg_lo:[1,0,0] neg_hi:[1,0,0]
	v_pk_fma_f32 v[152:153], v[148:149], v[156:157], v[154:155] neg_lo:[1,0,0] neg_hi:[1,0,0]
	v_pk_fma_f32 v[144:145], v[140:141], v[138:139], v[144:145]
	v_pk_fma_f32 v[156:157], v[152:153], v[150:151], v[156:157]
	v_pk_fma_f32 v[136:137], v[136:137], v[144:145], v[142:143] neg_lo:[1,0,0] neg_hi:[1,0,0]
	v_pk_fma_f32 v[148:149], v[148:149], v[156:157], v[154:155] neg_lo:[1,0,0] neg_hi:[1,0,0]
	s_mov_b64 vcc, s[28:29]
	v_div_fmas_f32 v136, v136, v138, v144
	s_mov_b64 vcc, s[30:31]
	v_div_fmas_f32 v137, v137, v139, v145
	s_mov_b64 vcc, s[2:3]
	v_div_fmas_f32 v148, v148, v150, v156
	s_mov_b64 vcc, s[100:101]
	v_div_fmas_f32 v149, v149, v151, v157
	v_div_fixup_f32 v134, v136, v134, v48
	v_div_fixup_f32 v135, v137, v135, v49
	v_div_fixup_f32 v146, v148, v146, v14
	v_div_fixup_f32 v147, v149, v147, v15
	v_cvt_pk_bf16_f32 v136, v134, v135
	v_cvt_pk_bf16_f32 v148, v146, v147
	ds_write_b16 v159, v136 offset:7200
	ds_write_b16_d16_hi v159, v136 offset:7472
	ds_write_b16 v159, v148 offset:7264
	ds_write_b16_d16_hi v159, v148 offset:7536
	s_mov_b64 s[100:101], 0x4000
	s_waitcnt lgkmcnt(0)
	ds_read_b128 v[164:167], v160 offset:0
	ds_read_b128 v[168:171], v160 offset:1088
	ds_read_b128 v[172:175], v160 offset:2176
	ds_read_b128 v[224:227], v160 offset:3264
	ds_read_b128 v[228:231], v160 offset:4352
	ds_read_b128 v[232:235], v160 offset:5440
	ds_read_b128 v[236:239], v160 offset:6528
	ds_read_b128 v[240:243], v160 offset:7616
	s_waitcnt lgkmcnt(7)
	global_store_dwordx4 v[162:163], v[164:167], off
	v_lshl_add_u64 v[162:163], v[162:163], 0, s[100:101]
	s_waitcnt lgkmcnt(6)
	global_store_dwordx4 v[162:163], v[168:171], off
	v_lshl_add_u64 v[162:163], v[162:163], 0, s[100:101]
	s_waitcnt lgkmcnt(5)
	global_store_dwordx4 v[162:163], v[172:175], off
	v_lshl_add_u64 v[162:163], v[162:163], 0, s[100:101]
	s_waitcnt lgkmcnt(4)
	global_store_dwordx4 v[162:163], v[224:227], off
	v_lshl_add_u64 v[162:163], v[162:163], 0, s[100:101]
	s_waitcnt lgkmcnt(3)
	global_store_dwordx4 v[162:163], v[228:231], off
	v_lshl_add_u64 v[162:163], v[162:163], 0, s[100:101]
	s_waitcnt lgkmcnt(2)
	global_store_dwordx4 v[162:163], v[232:235], off
	v_lshl_add_u64 v[162:163], v[162:163], 0, s[100:101]
	s_waitcnt lgkmcnt(1)
	global_store_dwordx4 v[162:163], v[236:239], off
	v_lshl_add_u64 v[162:163], v[162:163], 0, s[100:101]
	s_waitcnt lgkmcnt(0)
	global_store_dwordx4 v[162:163], v[240:243], off
	v_lshl_add_u64 v[162:163], v[162:163], 0, s[100:101]
	v_readlane_b32 s28, v249, 22
	v_readlane_b32 s29, v249, 23
	v_readlane_b32 s30, v249, 24
	v_readlane_b32 s31, v249, 25
	s_mov_b64 s[2:3], 0
